# DIFF attention: step blocks rewritten (ring-pipelined LDS fragments, in-place exp and bf16 pack, plain adds instead of packed adds beside MFMAs, next-tile row-max hoisted), far tiles skip max tree, ha
# speedup vs baseline: 1.0206x; 1.0050x over previous
; DI float fexp2(float x) { return __builtin_amdgcn_exp2f(x); }
; template <int DK, int DV, int MODE> ...
;     ...
;     float mx = fmaxf(st[0][0], st[1][0]);
; #pragma unroll
;     for (int i = 1; i < 16; ++i) mx = fmaxf(fmaxf(mx, st[0][i]), st[1][i]);
;     mx = fmaxf(mx, __shfl_xor(mx, 32));
;     const float mabs = mx + mbase;
;     if (__any(mabs > mrun + ATT_THR)) {
;       const float mn = fmaxf(mrun, mabs), alpha = fexp2(mrun - mn); mrun = mn; lsum *= alpha;
; #pragma unroll
;       for (int db = 0; db < DV / 32; ++db)
; #pragma unroll
;         for (int i = 0; i < 16; ++i) O[db][i] *= alpha;
;     }
;     const float delta = mrun - mbase;
;     if (__any(delta != 0.f)) {
; #pragma unroll
;       for (int kb = 0; kb < 2; ++kb)
; #pragma unroll
;         for (int i = 0; i < 16; ++i) st[kb][i] -= delta;
;     }
.Ld0_tree_a:
	v_max_f32_e32 v0, v80, v80
	v_max_f32_e32 v2, v96, v96
	v_max_f32_e32 v0, v2, v0
	v_max3_f32 v0, v0, v97, v81
	v_max3_f32 v0, v0, v98, v82
	v_max3_f32 v0, v0, v99, v83
	v_max3_f32 v0, v0, v100, v84
	v_max3_f32 v0, v0, v101, v85
	v_max3_f32 v0, v0, v102, v86
	v_max3_f32 v0, v0, v103, v87
	v_max3_f32 v0, v0, v104, v88
	v_max3_f32 v0, v0, v105, v89
	v_max3_f32 v0, v0, v106, v90
	v_max3_f32 v0, v0, v107, v91
	v_max3_f32 v0, v0, v108, v92
	v_max3_f32 v0, v0, v109, v93
	v_max3_f32 v0, v0, v110, v94
	v_max3_f32 v0, v0, v111, v95
	ds_bpermute_b32 v2, v179, v0
	s_waitcnt lgkmcnt(0)
	v_max_f32_e32 v2, v2, v2
	v_max_f32_e32 v174, v0, v2
.Ld0_join_a:
	v_pk_add_f32 v[2:3], v[192:193], v[174:175]
	s_nop 0
	v_cmp_gt_f32_e32 vcc, v2, v3
	s_cbranch_vccz .LBB0_132
	v_max_f32_e32 v0, v2, v2
	v_max_f32_e32 v2, v193, v193
	v_max_f32_e32 v2, v2, v0
	v_sub_f32_e32 v0, v193, v2
	v_exp_f32_e32 v0, v0
	v_mov_b32_e32 v193, v2
	v_mul_f32_e32 v241, v241, v0
	v_pk_mul_f32 v[78:79], v[78:79], v[0:1] op_sel_hi:[1,0]
	v_pk_mul_f32 v[76:77], v[76:77], v[0:1] op_sel_hi:[1,0]
	v_pk_mul_f32 v[74:75], v[74:75], v[0:1] op_sel_hi:[1,0]
	v_pk_mul_f32 v[72:73], v[72:73], v[0:1] op_sel_hi:[1,0]
	v_pk_mul_f32 v[70:71], v[70:71], v[0:1] op_sel_hi:[1,0]
	v_pk_mul_f32 v[68:69], v[68:69], v[0:1] op_sel_hi:[1,0]
	v_pk_mul_f32 v[66:67], v[66:67], v[0:1] op_sel_hi:[1,0]
	v_pk_mul_f32 v[64:65], v[64:65], v[0:1] op_sel_hi:[1,0]
	v_pk_mul_f32 v[62:63], v[62:63], v[0:1] op_sel_hi:[1,0]
	v_pk_mul_f32 v[60:61], v[60:61], v[0:1] op_sel_hi:[1,0]
	v_pk_mul_f32 v[58:59], v[58:59], v[0:1] op_sel_hi:[1,0]
	v_pk_mul_f32 v[56:57], v[56:57], v[0:1] op_sel_hi:[1,0]
	v_pk_mul_f32 v[54:55], v[54:55], v[0:1] op_sel_hi:[1,0]
	v_pk_mul_f32 v[52:53], v[52:53], v[0:1] op_sel_hi:[1,0]
	v_pk_mul_f32 v[50:51], v[50:51], v[0:1] op_sel_hi:[1,0]
	v_pk_mul_f32 v[48:49], v[48:49], v[0:1] op_sel_hi:[1,0]
	v_pk_mul_f32 v[46:47], v[46:47], v[0:1] op_sel_hi:[1,0]
	v_pk_mul_f32 v[44:45], v[44:45], v[0:1] op_sel_hi:[1,0]
	v_pk_mul_f32 v[42:43], v[42:43], v[0:1] op_sel_hi:[1,0]
	v_pk_mul_f32 v[40:41], v[40:41], v[0:1] op_sel_hi:[1,0]
	v_pk_mul_f32 v[38:39], v[38:39], v[0:1] op_sel_hi:[1,0]
	v_pk_mul_f32 v[36:37], v[36:37], v[0:1] op_sel_hi:[1,0]
	v_pk_mul_f32 v[34:35], v[34:35], v[0:1] op_sel_hi:[1,0]
	v_pk_mul_f32 v[32:33], v[32:33], v[0:1] op_sel_hi:[1,0]
	v_pk_mul_f32 v[30:31], v[30:31], v[0:1] op_sel_hi:[1,0]
	v_pk_mul_f32 v[28:29], v[28:29], v[0:1] op_sel_hi:[1,0]
	v_pk_mul_f32 v[26:27], v[26:27], v[0:1] op_sel_hi:[1,0]
	v_pk_mul_f32 v[24:25], v[24:25], v[0:1] op_sel_hi:[1,0]
	v_pk_mul_f32 v[22:23], v[22:23], v[0:1] op_sel_hi:[1,0]
	v_pk_mul_f32 v[20:21], v[20:21], v[0:1] op_sel_hi:[1,0]
	v_pk_mul_f32 v[18:19], v[18:19], v[0:1] op_sel_hi:[1,0]
	v_pk_mul_f32 v[16:17], v[16:17], v[0:1] op_sel_hi:[1,0]
.LBB0_132:
	v_sub_f32_e32 v0, v193, v192
	v_cmp_neq_f32_e32 vcc, 0, v0
	s_cbranch_vccz .LBB0_134
	v_pk_add_f32 v[96:97], v[96:97], v[0:1] op_sel_hi:[1,0] neg_lo:[0,1] neg_hi:[0,1]
	v_pk_add_f32 v[98:99], v[98:99], v[0:1] op_sel_hi:[1,0] neg_lo:[0,1] neg_hi:[0,1]
	v_pk_add_f32 v[100:101], v[100:101], v[0:1] op_sel_hi:[1,0] neg_lo:[0,1] neg_hi:[0,1]
	v_pk_add_f32 v[102:103], v[102:103], v[0:1] op_sel_hi:[1,0] neg_lo:[0,1] neg_hi:[0,1]
	v_pk_add_f32 v[104:105], v[104:105], v[0:1] op_sel_hi:[1,0] neg_lo:[0,1] neg_hi:[0,1]
	v_pk_add_f32 v[106:107], v[106:107], v[0:1] op_sel_hi:[1,0] neg_lo:[0,1] neg_hi:[0,1]
	v_pk_add_f32 v[108:109], v[108:109], v[0:1] op_sel_hi:[1,0] neg_lo:[0,1] neg_hi:[0,1]
	v_pk_add_f32 v[110:111], v[110:111], v[0:1] op_sel_hi:[1,0] neg_lo:[0,1] neg_hi:[0,1]
	v_pk_add_f32 v[80:81], v[80:81], v[0:1] op_sel_hi:[1,0] neg_lo:[0,1] neg_hi:[0,1]
	v_pk_add_f32 v[82:83], v[82:83], v[0:1] op_sel_hi:[1,0] neg_lo:[0,1] neg_hi:[0,1]
	v_pk_add_f32 v[84:85], v[84:85], v[0:1] op_sel_hi:[1,0] neg_lo:[0,1] neg_hi:[0,1]
	v_pk_add_f32 v[86:87], v[86:87], v[0:1] op_sel_hi:[1,0] neg_lo:[0,1] neg_hi:[0,1]
	v_pk_add_f32 v[88:89], v[88:89], v[0:1] op_sel_hi:[1,0] neg_lo:[0,1] neg_hi:[0,1]
	v_pk_add_f32 v[90:91], v[90:91], v[0:1] op_sel_hi:[1,0] neg_lo:[0,1] neg_hi:[0,1]
	v_pk_add_f32 v[92:93], v[92:93], v[0:1] op_sel_hi:[1,0] neg_lo:[0,1] neg_hi:[0,1]
	v_pk_add_f32 v[94:95], v[94:95], v[0:1] op_sel_hi:[1,0] neg_lo:[0,1] neg_hi:[0,1]
.LBB0_134:
	s_cmp_eq_u32 s32, 0
	s_cbranch_scc1 .Lstg_pre5
	s_waitcnt lgkmcnt(0)
	s_barrier
; #define LAS __attribute__((address_space(3)))
; DI float fexp2(float x) { return __builtin_amdgcn_exp2f(x); }
; template <int DK, int DV, int MODE> ...
;     ...
;   auto part1 = [&](f32x16 (&st)[2], float mbase, int t) __attribute__((always_inline)) {
;     if (MODE == 0) {
;       const int d0 = rel0 + 64 * t;
;       if (!(d0 - 31 >= 91) && !(d0 + 63 <= -91)) {
;         const int rb_ = d0 - r + 4 * hh + 128;
; #pragma unroll
;         for (int kb = 0; kb < 2; ++kb)
; #pragma unroll
;           for (int i = 0; i < 16; ++i) { int idx = rb_ + 32 * kb + (i & 3) + 8 * (i >> 2); idx = idx < 0 ? 0 : (idx > 256 ? 256 : idx); st[kb][i] += lut[idx]; }
;       }
;     } else {
;       const int ka = ka0 + t;
;       const LAS unsigned char* rp = (const LAS unsigned char*)lut + (ka - ri + 7) * 128;
; #pragma unroll
;       for (int q = 0; q < 8; ++q) { unsigned wv = nacolp[q]; asm volatile("" : "+v"(wv));
; #pragma unroll
;     ...
;   auto part2 = [&](f32x16 (&st)[2], int t) __attribute__((always_inline)) {
;     float ps0 = 0.f, ps1 = 0.f, ps2 = 0.f, ps3 = 0.f;
; #pragma unroll
;     for (int kb = 0; kb < 2; ++kb)
; #pragma unroll
;       for (int i = 0; i < 16; i += 4) {
;         const float p0 = fexp2(st[kb][i]), p1 = fexp2(st[kb][i + 1]), p2 = fexp2(st[kb][i + 2]), p3 = fexp2(st[kb][i + 3]);
;         st[kb][i] = p0; st[kb][i + 1] = p1; st[kb][i + 2] = p2; st[kb][i + 3] = p3; ps0 += p0; ps1 += p1; ps2 += p2; ps3 += p3;
;       }
;     lsum += (ps0 + ps1) + (ps2 + ps3);
;     bf16x8 pf[2][2];
; #pragma unroll
;     for (int kb = 0; kb < 2; ++kb)
; #pragma unroll
;       for (int s = 0; s < 2; ++s) { u32x4 pp; pp.x = cvt_pk(st[kb][8 * s], st[kb][8 * s + 1]); pp.y = cvt_pk(st[kb][8 * s + 2], st[kb][8 * s + 3]); pp.z = cvt_pk(st[kb][8 * s + 4], st[kb][8 * s + 5]); pp.w = cvt_pk(st[kb][8 * s + 6], st[kb][8 * s + 7]); pf[kb][s] = __builtin_bit_cast(bf16x8, pp); }
; #pragma unroll
;     for (int db = 0; db < DV / 32; ++db)
; #pragma unroll
;       for (int kb = 0; kb < 2; ++kb)
; #pragma unroll
;         for (int s = 0; s < 2; ++s) {
;           if (MODE == 1 && ((kb == 1 && s == 1 && cwu == 0) || (kb == 0 && s == 0 && cwu != 0))) continue;
;           const bf16x8 vf = *(const LAS bf16x8*)(lds + ATT_VB + (t & 3) * VBUF + (32 * db + r) * VSTR + (2 * kb + s) * 32 + hh * 16);
;           O[db] = __builtin_amdgcn_mfma_f32_32x32x16_bf16(vf, pf[kb][s], O[db], 0, 0, 0);
;         }
;   };
.Lstg_pre5:
	s_setprio 1
	s_add_i32 s73, s68, -4
	s_and_b32 s70, s73, 3
	s_mul_i32 s50, s70, 0x2400
	v_add_u32_e32 v3, s50, v235
	s_and_b32 s72, s72, 2
	s_mul_i32 s50, s72, 0x4800
	v_add_u32_e32 v224, s50, v237
	v_add_u32_e32 v224, 0xd000, v224
	ds_read_b128 v[4:7], v3
	ds_read_b128 v[8:11], v3 offset:32
	ds_read_b128 v[12:15], v3 offset:64
	ds_read_b128 v[196:199], v3 offset:96
	ds_read_b128 v[200:203], v3 offset:4608
	v_add_u32_e32 v0, 64, v242
	v_cmp_gt_i32_e64 s[50:51], s78, v0
	v_cmp_lt_i32_e32 vcc, s77, v0
	v_exp_f32_e32 v96, v96
	v_exp_f32_e32 v97, v97
	v_cndmask_b32_e64 v0, 0, v233, s[50:51]
	v_exp_f32_e32 v98, v98
	v_cndmask_b32_e32 v0, v0, v234, vcc
	v_cmp_neq_f32_e32 vcc, s53, v193
	v_exp_f32_e32 v99, v99
	v_exp_f32_e32 v100, v100
	v_exp_f32_e32 v101, v101
	v_cndmask_b32_e32 v2, 0, v193, vcc
	v_sub_f32_e32 v112, v0, v2
	v_mov_b32_e32 v113, v112
	v_mov_b32_e32 v114, v112
	v_mov_b32_e32 v115, v112
	v_mov_b32_e32 v116, v112
	v_mov_b32_e32 v117, v112
	v_mov_b32_e32 v118, v112
	v_mov_b32_e32 v119, v112
	v_mov_b32_e32 v120, v112
	v_mov_b32_e32 v121, v112
	v_mov_b32_e32 v122, v112
	v_mov_b32_e32 v123, v112
	v_mov_b32_e32 v124, v112
	v_mov_b32_e32 v125, v112
	v_mov_b32_e32 v126, v112
	v_mov_b32_e32 v127, v112
	v_exp_f32_e32 v102, v102
	v_exp_f32_e32 v103, v103
	s_waitcnt lgkmcnt(4)
	v_mfma_f32_32x32x16_bf16 v[128:143], v[4:7], v[144:147], v[112:127]
	ds_read_b128 v[4:7], v3 offset:4640
	v_add_f32_e32 v244, v96, v100
	v_add_f32_e32 v245, v97, v101
	v_add_f32_e32 v246, v98, v102
	v_add_f32_e32 v247, v99, v103
	v_cvt_pk_bf16_f32 v96, v96, v97
	v_cvt_pk_bf16_f32 v97, v98, v99
	v_cvt_pk_bf16_f32 v98, v100, v101
	s_waitcnt lgkmcnt(4)
	v_mfma_f32_32x32x16_bf16 v[128:143], v[8:11], v[148:151], v[128:143]
	ds_read_b128 v[8:11], v3 offset:4672
	v_cvt_pk_bf16_f32 v99, v102, v103
	v_exp_f32_e32 v104, v104
	v_exp_f32_e32 v105, v105
	v_exp_f32_e32 v106, v106
	s_waitcnt lgkmcnt(4)
	v_mfma_f32_32x32x16_bf16 v[128:143], v[12:15], v[152:155], v[128:143]
	ds_read_b128 v[12:15], v3 offset:4704
	v_exp_f32_e32 v107, v107
	v_exp_f32_e32 v108, v108
	v_exp_f32_e32 v109, v109
	v_exp_f32_e32 v110, v110
	s_waitcnt lgkmcnt(4)
	v_mfma_f32_32x32x16_bf16 v[128:143], v[196:199], v[156:159], v[128:143]
	ds_read_b128 v[196:199], v224
	v_exp_f32_e32 v111, v111
	v_add_f32_e32 v244, v104, v244
	v_add_f32_e32 v245, v105, v245
	v_add_f32_e32 v246, v106, v246
	v_add_f32_e32 v247, v107, v247
	v_add_f32_e32 v244, v108, v244
	s_waitcnt lgkmcnt(4)
	v_mfma_f32_32x32x16_bf16 v[112:127], v[200:203], v[144:147], v[112:127]
	ds_read_b128 v[200:203], v224 offset:4608
	v_add_f32_e32 v245, v109, v245
	v_add_f32_e32 v246, v110, v246
	v_add_f32_e32 v247, v111, v247
	v_cvt_pk_bf16_f32 v104, v104, v105
	v_cvt_pk_bf16_f32 v105, v106, v107
	v_cvt_pk_bf16_f32 v106, v108, v109
	v_cvt_pk_bf16_f32 v107, v110, v111
	s_waitcnt lgkmcnt(4)
	v_mfma_f32_32x32x16_bf16 v[112:127], v[4:7], v[148:151], v[112:127]
	ds_read_b128 v[4:7], v224 offset:9216
	v_exp_f32_e32 v80, v80
	v_exp_f32_e32 v81, v81
	v_exp_f32_e32 v82, v82
	v_exp_f32_e32 v83, v83
	s_waitcnt lgkmcnt(4)
	v_mfma_f32_32x32x16_bf16 v[112:127], v[8:11], v[152:155], v[112:127]
	ds_read_b128 v[8:11], v224 offset:13824
	v_exp_f32_e32 v84, v84
	v_exp_f32_e32 v85, v85
	v_exp_f32_e32 v86, v86
	v_exp_f32_e32 v87, v87
	s_waitcnt lgkmcnt(4)
	v_mfma_f32_32x32x16_bf16 v[112:127], v[12:15], v[156:159], v[112:127]
	ds_read_b128 v[12:15], v224 offset:32
	v_add_f32_e32 v244, v80, v244
	v_add_f32_e32 v245, v81, v245
	v_add_f32_e32 v246, v82, v246
	v_add_f32_e32 v247, v83, v247
	v_add_f32_e32 v244, v84, v244
	v_add_f32_e32 v245, v85, v245
	v_add_f32_e32 v246, v86, v246
	s_waitcnt lgkmcnt(4)
	v_mfma_f32_32x32x16_bf16 v[64:79], v[196:199], v[96:99], v[64:79]
	ds_read_b128 v[196:199], v224 offset:4640
	v_add_f32_e32 v247, v87, v247
	v_cvt_pk_bf16_f32 v80, v80, v81
	v_cvt_pk_bf16_f32 v81, v82, v83
	v_cvt_pk_bf16_f32 v82, v84, v85
	v_cvt_pk_bf16_f32 v83, v86, v87
	v_exp_f32_e32 v88, v88
	s_waitcnt lgkmcnt(4)
	v_mfma_f32_32x32x16_bf16 v[48:63], v[200:203], v[96:99], v[48:63]
	ds_read_b128 v[200:203], v224 offset:9248
	v_exp_f32_e32 v89, v89
	v_exp_f32_e32 v90, v90
	v_exp_f32_e32 v91, v91
	v_exp_f32_e32 v92, v92
	s_waitcnt lgkmcnt(4)
	v_mfma_f32_32x32x16_bf16 v[32:47], v[4:7], v[96:99], v[32:47]
	ds_read_b128 v[4:7], v224 offset:13856
	v_exp_f32_e32 v93, v93
	v_exp_f32_e32 v94, v94
	v_exp_f32_e32 v95, v95
	v_add_f32_e32 v244, v88, v244
	s_waitcnt lgkmcnt(4)
	v_mfma_f32_32x32x16_bf16 v[16:31], v[8:11], v[96:99], v[16:31]
	ds_read_b128 v[8:11], v224 offset:64
	v_add_f32_e32 v245, v89, v245
	v_add_f32_e32 v246, v90, v246
	v_add_f32_e32 v247, v91, v247
	v_add_f32_e32 v244, v92, v244
	v_add_f32_e32 v245, v93, v245
	v_add_f32_e32 v246, v94, v246
	v_add_f32_e32 v247, v95, v247
	s_waitcnt lgkmcnt(4)
	v_mfma_f32_32x32x16_bf16 v[64:79], v[12:15], v[104:107], v[64:79]
	ds_read_b128 v[12:15], v224 offset:4672
	v_cvt_pk_bf16_f32 v88, v88, v89
	v_cvt_pk_bf16_f32 v89, v90, v91
	v_cvt_pk_bf16_f32 v90, v92, v93
	v_cvt_pk_bf16_f32 v91, v94, v95
	v_add_f32_e32 v244, v244, v245
	v_add_f32_e32 v246, v246, v247
	v_max3_f32 v248, v128, v129, v130
	s_waitcnt lgkmcnt(4)
	v_mfma_f32_32x32x16_bf16 v[48:63], v[196:199], v[104:107], v[48:63]
	ds_read_b128 v[196:199], v224 offset:9280
	v_max3_f32 v249, v135, v136, v137
	v_max3_f32 v248, v248, v131, v132
	v_max3_f32 v249, v249, v138, v139
	v_max3_f32 v248, v248, v133, v134
	v_max3_f32 v249, v249, v140, v141
	v_max3_f32 v250, v112, v113, v114
	v_max3_f32 v251, v119, v120, v121
	s_waitcnt lgkmcnt(4)
	v_mfma_f32_32x32x16_bf16 v[32:47], v[200:203], v[104:107], v[32:47]
	ds_read_b128 v[200:203], v224 offset:13888
	v_max3_f32 v250, v250, v115, v116
	v_max3_f32 v251, v251, v122, v123
	v_max3_f32 v250, v250, v117, v118
	v_max3_f32 v251, v251, v124, v125
	v_max3_f32 v248, v248, v249, v142
	v_max3_f32 v250, v250, v251, v126
	v_max3_f32 v248, v248, v143, v127
	s_waitcnt lgkmcnt(4)
	v_mfma_f32_32x32x16_bf16 v[16:31], v[4:7], v[104:107], v[16:31]
	ds_read_b128 v[4:7], v224 offset:96
	v_max_f32_e32 v248, v248, v250
	v_mov_b32_e32 v249, v248
	s_waitcnt lgkmcnt(4)
	v_mfma_f32_32x32x16_bf16 v[64:79], v[8:11], v[80:83], v[64:79]
	ds_read_b128 v[8:11], v224 offset:4704
	s_waitcnt lgkmcnt(4)
	v_mfma_f32_32x32x16_bf16 v[48:63], v[12:15], v[80:83], v[48:63]
	ds_read_b128 v[12:15], v224 offset:9312
	s_waitcnt lgkmcnt(4)
	v_mfma_f32_32x32x16_bf16 v[32:47], v[196:199], v[80:83], v[32:47]
	ds_read_b128 v[196:199], v224 offset:13920
	s_waitcnt lgkmcnt(4)
	v_mfma_f32_32x32x16_bf16 v[16:31], v[200:203], v[80:83], v[16:31]
	s_waitcnt lgkmcnt(3)
	v_mfma_f32_32x32x16_bf16 v[64:79], v[4:7], v[88:91], v[64:79]
	s_waitcnt lgkmcnt(2)
	v_mfma_f32_32x32x16_bf16 v[48:63], v[8:11], v[88:91], v[48:63]
	s_waitcnt lgkmcnt(1)
	v_mfma_f32_32x32x16_bf16 v[32:47], v[12:15], v[88:91], v[32:47]
	s_waitcnt lgkmcnt(0)
	v_mfma_f32_32x32x16_bf16 v[16:31], v[196:199], v[88:91], v[16:31]
	v_add_f32_e32 v0, v244, v246
	v_add_f32_e32 v241, v241, v0
	v_permlane32_swap_b32 v248, v249
	v_max_f32_e32 v174, v248, v249
	s_setprio 0
	s_cmp_lg_u32 s32, 0
	s_cbranch_scc1 .Lstg_post6
	s_waitcnt lgkmcnt(0)
	s_barrier
.Lstg_post6:
	s_cmp_ge_u32 s73, s38
	s_cbranch_scc1 .LBB0_118
	s_and_saveexec_b64 s[50:51], s[60:61]
	s_cbranch_execz .LBB0_137
	s_mulk_i32 s72, 0x2400
	v_add_u32_e32 v0, s72, v185
	s_waitcnt vmcnt(0)
	ds_write_b128 v0, v[160:163]

; #define LAS __attribute__((address_space(3)))
; DI unsigned cvt_pk(float lo, float hi) { unsigned r; asm volatile("v_cvt_pk_bf16_f32 %0, %1, %2" : "=v"(r) : "v"(lo), "v"(hi)); return r; }
; DI float fexp2(float x) { return __builtin_amdgcn_exp2f(x); }
; template <int DK, int DV, int MODE> ...
;     ...
;     const float mabs = mx + mbase;
;     if (__any(mabs > mrun + ATT_THR)) {
;       const float mn = fmaxf(mrun, mabs), alpha = fexp2(mrun - mn); mrun = mn; lsum *= alpha;
; #pragma unroll
;       for (int db = 0; db < DV / 32; ++db)
; #pragma unroll
;         for (int i = 0; i < 16; ++i) O[db][i] *= alpha;
;     }
;     const float delta = mrun - mbase;
;     if (__any(delta != 0.f)) {
; #pragma unroll
;       for (int kb = 0; kb < 2; ++kb)
; #pragma unroll
;         for (int i = 0; i < 16; ++i) st[kb][i] -= delta;
;     }
;   };
;   auto part2 = [&](f32x16 (&st)[2], int t) __attribute__((always_inline)) {
;     float ps0 = 0.f, ps1 = 0.f, ps2 = 0.f, ps3 = 0.f;
; #pragma unroll
;     for (int kb = 0; kb < 2; ++kb)
; #pragma unroll
;       for (int i = 0; i < 16; i += 4) {
;         const float p0 = fexp2(st[kb][i]), p1 = fexp2(st[kb][i + 1]), p2 = fexp2(st[kb][i + 2]), p3 = fexp2(st[kb][i + 3]);
;         st[kb][i] = p0; st[kb][i + 1] = p1; st[kb][i + 2] = p2; st[kb][i + 3] = p3; ps0 += p0; ps1 += p1; ps2 += p2; ps3 += p3;
;       }
;     lsum += (ps0 + ps1) + (ps2 + ps3);
;     bf16x8 pf[2][2];
; #pragma unroll
;     for (int kb = 0; kb < 2; ++kb)
; #pragma unroll
;       for (int s = 0; s < 2; ++s) { u32x4 pp; pp.x = cvt_pk(st[kb][8 * s], st[kb][8 * s + 1]); pp.y = cvt_pk(st[kb][8 * s + 2], st[kb][8 * s + 3]); pp.z = cvt_pk(st[kb][8 * s + 4], st[kb][8 * s + 5]); pp.w = cvt_pk(st[kb][8 * s + 6], st[kb][8 * s + 7]); pf[kb][s] = __builtin_bit_cast(bf16x8, pp); }
; #pragma unroll
;     for (int db = 0; db < DV / 32; ++db)
; #pragma unroll
;       for (int kb = 0; kb < 2; ++kb)
; #pragma unroll
;         for (int s = 0; s < 2; ++s) {
;           if (MODE == 1 && ((kb == 1 && s == 1 && cwu == 0) || (kb == 0 && s == 0 && cwu != 0))) continue;
;           const bf16x8 vf = *(const LAS bf16x8*)(lds + ATT_VB + (t & 3) * VBUF + (32 * db + r) * VSTR + (2 * kb + s) * 32 + hh * 16);
;           O[db] = __builtin_amdgcn_mfma_f32_32x32x16_bf16(vf, pf[kb][s], O[db], 0, 0, 0);
;         }
;   };
.Ld0_join_b:
	v_mov_b32_e32 v3, v193
	v_pk_add_f32 v[4:5], v[2:3], v[174:175]
	s_nop 0
	v_cmp_gt_f32_e32 vcc, v4, v5
	s_cbranch_vccz .LBB0_145
	v_max_f32_e32 v0, v4, v4
	v_max_f32_e32 v3, v193, v193
	v_max_f32_e32 v3, v3, v0
	v_sub_f32_e32 v0, v193, v3
	v_exp_f32_e32 v0, v0
	v_mov_b32_e32 v193, v3
	v_mul_f32_e32 v241, v241, v0
	v_pk_mul_f32 v[78:79], v[78:79], v[0:1] op_sel_hi:[1,0]
	v_pk_mul_f32 v[76:77], v[76:77], v[0:1] op_sel_hi:[1,0]
	v_pk_mul_f32 v[74:75], v[74:75], v[0:1] op_sel_hi:[1,0]
	v_pk_mul_f32 v[72:73], v[72:73], v[0:1] op_sel_hi:[1,0]
	v_pk_mul_f32 v[70:71], v[70:71], v[0:1] op_sel_hi:[1,0]
	v_pk_mul_f32 v[68:69], v[68:69], v[0:1] op_sel_hi:[1,0]
	v_pk_mul_f32 v[66:67], v[66:67], v[0:1] op_sel_hi:[1,0]
	v_pk_mul_f32 v[64:65], v[64:65], v[0:1] op_sel_hi:[1,0]
	v_pk_mul_f32 v[62:63], v[62:63], v[0:1] op_sel_hi:[1,0]
	v_pk_mul_f32 v[60:61], v[60:61], v[0:1] op_sel_hi:[1,0]
	v_pk_mul_f32 v[58:59], v[58:59], v[0:1] op_sel_hi:[1,0]
	v_pk_mul_f32 v[56:57], v[56:57], v[0:1] op_sel_hi:[1,0]
	v_pk_mul_f32 v[54:55], v[54:55], v[0:1] op_sel_hi:[1,0]
	v_pk_mul_f32 v[52:53], v[52:53], v[0:1] op_sel_hi:[1,0]
	v_pk_mul_f32 v[50:51], v[50:51], v[0:1] op_sel_hi:[1,0]
	v_pk_mul_f32 v[48:49], v[48:49], v[0:1] op_sel_hi:[1,0]
	v_pk_mul_f32 v[46:47], v[46:47], v[0:1] op_sel_hi:[1,0]
	v_pk_mul_f32 v[44:45], v[44:45], v[0:1] op_sel_hi:[1,0]
	v_pk_mul_f32 v[42:43], v[42:43], v[0:1] op_sel_hi:[1,0]
	v_pk_mul_f32 v[40:41], v[40:41], v[0:1] op_sel_hi:[1,0]
	v_pk_mul_f32 v[38:39], v[38:39], v[0:1] op_sel_hi:[1,0]
	v_pk_mul_f32 v[36:37], v[36:37], v[0:1] op_sel_hi:[1,0]
	v_pk_mul_f32 v[34:35], v[34:35], v[0:1] op_sel_hi:[1,0]
	v_pk_mul_f32 v[32:33], v[32:33], v[0:1] op_sel_hi:[1,0]
	v_pk_mul_f32 v[30:31], v[30:31], v[0:1] op_sel_hi:[1,0]
	v_pk_mul_f32 v[28:29], v[28:29], v[0:1] op_sel_hi:[1,0]
	v_pk_mul_f32 v[26:27], v[26:27], v[0:1] op_sel_hi:[1,0]
	v_pk_mul_f32 v[24:25], v[24:25], v[0:1] op_sel_hi:[1,0]
	v_pk_mul_f32 v[22:23], v[22:23], v[0:1] op_sel_hi:[1,0]
	v_pk_mul_f32 v[20:21], v[20:21], v[0:1] op_sel_hi:[1,0]
	v_pk_mul_f32 v[18:19], v[18:19], v[0:1] op_sel_hi:[1,0]
	v_pk_mul_f32 v[16:17], v[16:17], v[0:1] op_sel_hi:[1,0]
.LBB0_145:
	v_sub_f32_e32 v0, v193, v2
	v_cmp_neq_f32_e32 vcc, 0, v0
	s_cbranch_vccz .LBB0_147
	v_pk_add_f32 v[128:129], v[128:129], v[0:1] op_sel_hi:[1,0] neg_lo:[0,1] neg_hi:[0,1]
	v_pk_add_f32 v[130:131], v[130:131], v[0:1] op_sel_hi:[1,0] neg_lo:[0,1] neg_hi:[0,1]
	v_pk_add_f32 v[132:133], v[132:133], v[0:1] op_sel_hi:[1,0] neg_lo:[0,1] neg_hi:[0,1]
	v_pk_add_f32 v[134:135], v[134:135], v[0:1] op_sel_hi:[1,0] neg_lo:[0,1] neg_hi:[0,1]
	v_pk_add_f32 v[136:137], v[136:137], v[0:1] op_sel_hi:[1,0] neg_lo:[0,1] neg_hi:[0,1]
	v_pk_add_f32 v[138:139], v[138:139], v[0:1] op_sel_hi:[1,0] neg_lo:[0,1] neg_hi:[0,1]
	v_pk_add_f32 v[140:141], v[140:141], v[0:1] op_sel_hi:[1,0] neg_lo:[0,1] neg_hi:[0,1]
	v_pk_add_f32 v[142:143], v[142:143], v[0:1] op_sel_hi:[1,0] neg_lo:[0,1] neg_hi:[0,1]
	v_pk_add_f32 v[112:113], v[112:113], v[0:1] op_sel_hi:[1,0] neg_lo:[0,1] neg_hi:[0,1]
	v_pk_add_f32 v[114:115], v[114:115], v[0:1] op_sel_hi:[1,0] neg_lo:[0,1] neg_hi:[0,1]
	v_pk_add_f32 v[116:117], v[116:117], v[0:1] op_sel_hi:[1,0] neg_lo:[0,1] neg_hi:[0,1]
	v_pk_add_f32 v[118:119], v[118:119], v[0:1] op_sel_hi:[1,0] neg_lo:[0,1] neg_hi:[0,1]
	v_pk_add_f32 v[120:121], v[120:121], v[0:1] op_sel_hi:[1,0] neg_lo:[0,1] neg_hi:[0,1]
	v_pk_add_f32 v[122:123], v[122:123], v[0:1] op_sel_hi:[1,0] neg_lo:[0,1] neg_hi:[0,1]
	v_pk_add_f32 v[124:125], v[124:125], v[0:1] op_sel_hi:[1,0] neg_lo:[0,1] neg_hi:[0,1]
	v_pk_add_f32 v[126:127], v[126:127], v[0:1] op_sel_hi:[1,0] neg_lo:[0,1] neg_hi:[0,1]
.LBB0_147:
	s_cmp_eq_u32 s32, 0
	s_cbranch_scc1 .Lstg_pre7
	s_waitcnt lgkmcnt(0)
	s_barrier
.Lstg_pre7:
	s_setprio 1
	s_and_b32 s40, s69, 2
	s_mulk_i32 s40, 0x2400
	s_mulk_i32 s70, 0x4800
	v_add_u32_e32 v3, s40, v235
	v_add_u32_e32 v224, s70, v237
	v_add_u32_e32 v224, 0xd000, v224
	ds_read_b128 v[4:7], v3
	ds_read_b128 v[8:11], v3 offset:32
	ds_read_b128 v[12:15], v3 offset:64
	ds_read_b128 v[196:199], v3 offset:96
	ds_read_b128 v[200:203], v3 offset:4608
	v_add_u32_e32 v0, 0x80, v242
	v_cmp_gt_i32_e32 vcc, s78, v0
	v_exp_f32_e32 v128, v128
	v_exp_f32_e32 v129, v129
	v_cndmask_b32_e32 v2, 0, v233, vcc
	v_cmp_lt_i32_e32 vcc, s77, v0
	v_exp_f32_e32 v130, v130
	v_exp_f32_e32 v131, v131
	v_cndmask_b32_e32 v0, v2, v234, vcc
	v_cmp_neq_f32_e32 vcc, s53, v193
	v_exp_f32_e32 v132, v132
	v_exp_f32_e32 v133, v133
	v_cndmask_b32_e32 v192, 0, v193, vcc
	v_sub_f32_e32 v80, v0, v192
	v_mov_b32_e32 v81, v80
	v_mov_b32_e32 v82, v80
	v_mov_b32_e32 v83, v80
	v_mov_b32_e32 v84, v80
	v_mov_b32_e32 v85, v80
	v_mov_b32_e32 v86, v80
	v_mov_b32_e32 v87, v80
	v_mov_b32_e32 v88, v80
	v_mov_b32_e32 v89, v80
	v_mov_b32_e32 v90, v80
	v_mov_b32_e32 v91, v80
	v_mov_b32_e32 v92, v80
	v_mov_b32_e32 v93, v80
	v_mov_b32_e32 v94, v80
	v_mov_b32_e32 v95, v80
	v_exp_f32_e32 v134, v134
	v_exp_f32_e32 v135, v135
	s_waitcnt lgkmcnt(4)
	v_mfma_f32_32x32x16_bf16 v[96:111], v[4:7], v[144:147], v[80:95]
	ds_read_b128 v[4:7], v3 offset:4640
	v_add_f32_e32 v244, v128, v132
	v_add_f32_e32 v245, v129, v133
	v_add_f32_e32 v246, v130, v134
	v_add_f32_e32 v247, v131, v135
	v_cvt_pk_bf16_f32 v128, v128, v129
	v_cvt_pk_bf16_f32 v129, v130, v131
	v_cvt_pk_bf16_f32 v130, v132, v133
	s_waitcnt lgkmcnt(4)
	v_mfma_f32_32x32x16_bf16 v[96:111], v[8:11], v[148:151], v[96:111]
	ds_read_b128 v[8:11], v3 offset:4672
	v_cvt_pk_bf16_f32 v131, v134, v135
	v_exp_f32_e32 v136, v136
	v_exp_f32_e32 v137, v137
	v_exp_f32_e32 v138, v138
	s_waitcnt lgkmcnt(4)
; #define LAS __attribute__((address_space(3)))
; DI unsigned cvt_pk(float lo, float hi) { unsigned r; asm volatile("v_cvt_pk_bf16_f32 %0, %1, %2" : "=v"(r) : "v"(lo), "v"(hi)); return r; }
; DI float fexp2(float x) { return __builtin_amdgcn_exp2f(x); }
; template <int DK, int DV, int MODE> ...
;     ...
;     float mx = fmaxf(st[0][0], st[1][0]);
; #pragma unroll
;     for (int i = 1; i < 16; ++i) mx = fmaxf(fmaxf(mx, st[0][i]), st[1][i]);
;     mx = fmaxf(mx, __shfl_xor(mx, 32));
;     ...
;   auto part2 = [&](f32x16 (&st)[2], int t) __attribute__((always_inline)) {
;     float ps0 = 0.f, ps1 = 0.f, ps2 = 0.f, ps3 = 0.f;
; #pragma unroll
;     for (int kb = 0; kb < 2; ++kb)
; #pragma unroll
;       for (int i = 0; i < 16; i += 4) {
;         const float p0 = fexp2(st[kb][i]), p1 = fexp2(st[kb][i + 1]), p2 = fexp2(st[kb][i + 2]), p3 = fexp2(st[kb][i + 3]);
;         st[kb][i] = p0; st[kb][i + 1] = p1; st[kb][i + 2] = p2; st[kb][i + 3] = p3; ps0 += p0; ps1 += p1; ps2 += p2; ps3 += p3;
;       }
;     lsum += (ps0 + ps1) + (ps2 + ps3);
;     bf16x8 pf[2][2];
; #pragma unroll
;     for (int kb = 0; kb < 2; ++kb)
; #pragma unroll
;       for (int s = 0; s < 2; ++s) { u32x4 pp; pp.x = cvt_pk(st[kb][8 * s], st[kb][8 * s + 1]); pp.y = cvt_pk(st[kb][8 * s + 2], st[kb][8 * s + 3]); pp.z = cvt_pk(st[kb][8 * s + 4], st[kb][8 * s + 5]); pp.w = cvt_pk(st[kb][8 * s + 6], st[kb][8 * s + 7]); pf[kb][s] = __builtin_bit_cast(bf16x8, pp); }
; #pragma unroll
;     for (int db = 0; db < DV / 32; ++db)
; #pragma unroll
;       for (int kb = 0; kb < 2; ++kb)
; #pragma unroll
;         for (int s = 0; s < 2; ++s) {
;           if (MODE == 1 && ((kb == 1 && s == 1 && cwu == 0) || (kb == 0 && s == 0 && cwu != 0))) continue;
;           const bf16x8 vf = *(const LAS bf16x8*)(lds + ATT_VB + (t & 3) * VBUF + (32 * db + r) * VSTR + (2 * kb + s) * 32 + hh * 16);
;           O[db] = __builtin_amdgcn_mfma_f32_32x32x16_bf16(vf, pf[kb][s], O[db], 0, 0, 0);
;         }
;   };
	v_mfma_f32_32x32x16_bf16 v[96:111], v[12:15], v[152:155], v[96:111]
	ds_read_b128 v[12:15], v3 offset:4704
	v_exp_f32_e32 v139, v139
	v_exp_f32_e32 v140, v140
	v_exp_f32_e32 v141, v141
	v_exp_f32_e32 v142, v142
	s_waitcnt lgkmcnt(4)
	v_mfma_f32_32x32x16_bf16 v[96:111], v[196:199], v[156:159], v[96:111]
	ds_read_b128 v[196:199], v224
	v_exp_f32_e32 v143, v143
	v_add_f32_e32 v244, v136, v244
	v_add_f32_e32 v245, v137, v245
	v_add_f32_e32 v246, v138, v246
	v_add_f32_e32 v247, v139, v247
	v_add_f32_e32 v244, v140, v244
	s_waitcnt lgkmcnt(4)
	v_mfma_f32_32x32x16_bf16 v[80:95], v[200:203], v[144:147], v[80:95]
	ds_read_b128 v[200:203], v224 offset:4608
	v_add_f32_e32 v245, v141, v245
	v_add_f32_e32 v246, v142, v246
	v_add_f32_e32 v247, v143, v247
	v_cvt_pk_bf16_f32 v136, v136, v137
	v_cvt_pk_bf16_f32 v137, v138, v139
	v_cvt_pk_bf16_f32 v138, v140, v141
	v_cvt_pk_bf16_f32 v139, v142, v143
	s_waitcnt lgkmcnt(4)
	v_mfma_f32_32x32x16_bf16 v[80:95], v[4:7], v[148:151], v[80:95]
	ds_read_b128 v[4:7], v224 offset:9216
	v_exp_f32_e32 v112, v112
	v_exp_f32_e32 v113, v113
	v_exp_f32_e32 v114, v114
	v_exp_f32_e32 v115, v115
	s_waitcnt lgkmcnt(4)
	v_mfma_f32_32x32x16_bf16 v[80:95], v[8:11], v[152:155], v[80:95]
	ds_read_b128 v[8:11], v224 offset:13824
	v_exp_f32_e32 v116, v116
	v_exp_f32_e32 v117, v117
	v_exp_f32_e32 v118, v118
	v_exp_f32_e32 v119, v119
	s_waitcnt lgkmcnt(4)
	v_mfma_f32_32x32x16_bf16 v[80:95], v[12:15], v[156:159], v[80:95]
	ds_read_b128 v[12:15], v224 offset:32
	v_add_f32_e32 v244, v112, v244
	v_add_f32_e32 v245, v113, v245
	v_add_f32_e32 v246, v114, v246
	v_add_f32_e32 v247, v115, v247
	v_add_f32_e32 v244, v116, v244
	v_add_f32_e32 v245, v117, v245
	v_add_f32_e32 v246, v118, v246
	s_waitcnt lgkmcnt(4)
	v_mfma_f32_32x32x16_bf16 v[64:79], v[196:199], v[128:131], v[64:79]
	ds_read_b128 v[196:199], v224 offset:4640
	v_add_f32_e32 v247, v119, v247
	v_cvt_pk_bf16_f32 v112, v112, v113
	v_cvt_pk_bf16_f32 v113, v114, v115
	v_cvt_pk_bf16_f32 v114, v116, v117
	v_cvt_pk_bf16_f32 v115, v118, v119
	v_exp_f32_e32 v120, v120
	s_waitcnt lgkmcnt(4)
	v_mfma_f32_32x32x16_bf16 v[48:63], v[200:203], v[128:131], v[48:63]
	ds_read_b128 v[200:203], v224 offset:9248
	v_exp_f32_e32 v121, v121
	v_exp_f32_e32 v122, v122
	v_exp_f32_e32 v123, v123
	v_exp_f32_e32 v124, v124
	s_waitcnt lgkmcnt(4)
	v_mfma_f32_32x32x16_bf16 v[32:47], v[4:7], v[128:131], v[32:47]
	ds_read_b128 v[4:7], v224 offset:13856
	v_exp_f32_e32 v125, v125
	v_exp_f32_e32 v126, v126
	v_exp_f32_e32 v127, v127
	v_add_f32_e32 v244, v120, v244
	s_waitcnt lgkmcnt(4)
	v_mfma_f32_32x32x16_bf16 v[16:31], v[8:11], v[128:131], v[16:31]
	ds_read_b128 v[8:11], v224 offset:64
	v_add_f32_e32 v245, v121, v245
	v_add_f32_e32 v246, v122, v246
	v_add_f32_e32 v247, v123, v247
	v_add_f32_e32 v244, v124, v244
	v_add_f32_e32 v245, v125, v245
	v_add_f32_e32 v246, v126, v246
	v_add_f32_e32 v247, v127, v247
	s_waitcnt lgkmcnt(4)
	v_mfma_f32_32x32x16_bf16 v[64:79], v[12:15], v[136:139], v[64:79]
	ds_read_b128 v[12:15], v224 offset:4672
	v_cvt_pk_bf16_f32 v120, v120, v121
	v_cvt_pk_bf16_f32 v121, v122, v123
	v_cvt_pk_bf16_f32 v122, v124, v125
	v_cvt_pk_bf16_f32 v123, v126, v127
	v_add_f32_e32 v244, v244, v245
	v_add_f32_e32 v246, v246, v247
	v_max3_f32 v248, v96, v97, v98
	s_waitcnt lgkmcnt(4)
	v_mfma_f32_32x32x16_bf16 v[48:63], v[196:199], v[136:139], v[48:63]
	ds_read_b128 v[196:199], v224 offset:9280
	v_max3_f32 v249, v103, v104, v105
	v_max3_f32 v248, v248, v99, v100
	v_max3_f32 v249, v249, v106, v107
	v_max3_f32 v248, v248, v101, v102
	v_max3_f32 v249, v249, v108, v109
	v_max3_f32 v250, v80, v81, v82
	v_max3_f32 v251, v87, v88, v89
	s_waitcnt lgkmcnt(4)
	v_mfma_f32_32x32x16_bf16 v[32:47], v[200:203], v[136:139], v[32:47]
	ds_read_b128 v[200:203], v224 offset:13888
	v_max3_f32 v250, v250, v83, v84
	v_max3_f32 v251, v251, v90, v91
	v_max3_f32 v250, v250, v85, v86
	v_max3_f32 v251, v251, v92, v93
	v_max3_f32 v248, v248, v249, v110
	v_max3_f32 v250, v250, v251, v94
	v_max3_f32 v248, v248, v111, v95
	s_waitcnt lgkmcnt(4)
	v_mfma_f32_32x32x16_bf16 v[16:31], v[4:7], v[136:139], v[16:31]
	ds_read_b128 v[4:7], v224 offset:96
	v_max_f32_e32 v248, v248, v250
	v_mov_b32_e32 v249, v248
	s_waitcnt lgkmcnt(4)
	v_mfma_f32_32x32x16_bf16 v[64:79], v[8:11], v[112:115], v[64:79]
	ds_read_b128 v[8:11], v224 offset:4704
	s_waitcnt lgkmcnt(4)
	v_mfma_f32_32x32x16_bf16 v[48:63], v[12:15], v[112:115], v[48:63]
	ds_read_b128 v[12:15], v224 offset:9312
	s_waitcnt lgkmcnt(4)
	v_mfma_f32_32x32x16_bf16 v[32:47], v[196:199], v[112:115], v[32:47]
	ds_read_b128 v[196:199], v224 offset:13920
	s_waitcnt lgkmcnt(4)
	v_mfma_f32_32x32x16_bf16 v[16:31], v[200:203], v[112:115], v[16:31]
	s_waitcnt lgkmcnt(3)
	v_mfma_f32_32x32x16_bf16 v[64:79], v[4:7], v[120:123], v[64:79]
	s_waitcnt lgkmcnt(2)
	v_mfma_f32_32x32x16_bf16 v[48:63], v[8:11], v[120:123], v[48:63]
	s_waitcnt lgkmcnt(1)
	v_mfma_f32_32x32x16_bf16 v[32:47], v[12:15], v[120:123], v[32:47]
	s_waitcnt lgkmcnt(0)
	v_mfma_f32_32x32x16_bf16 v[16:31], v[196:199], v[120:123], v[16:31]
	v_add_f32_e32 v0, v244, v246
	v_add_f32_e32 v241, v241, v0
	v_permlane32_swap_b32 v248, v249
	v_max_f32_e32 v174, v248, v249
	s_setprio 0
	s_cmp_lg_u32 s32, 0
	s_cbranch_scc1 .Lstg_post8
	s_waitcnt lgkmcnt(0)
	s_barrier
.Lstg_post8:
	s_branch .LBB0_119
.LBB0_148:
	global_load_dwordx4 v[160:163], v[190:191], off
	s_or_b64 exec, exec, s[48:49]
	s_andn2_b64 vcc, exec, s[40:41]
	s_cbranch_vccnz .LBB0_141

; template <int DK, int DV, int MODE> ...
;     ...
;   auto part1 = [&](f32x16 (&st)[2], float mbase, int t) __attribute__((always_inline)) {
;     if (MODE == 0) {
;       const int d0 = rel0 + 64 * t;
;       if (!(d0 - 31 >= 91) && !(d0 + 63 <= -91)) {
;         const int rb_ = d0 - r + 4 * hh + 128;
; #pragma unroll
;         for (int kb = 0; kb < 2; ++kb)
; #pragma unroll
;           for (int i = 0; i < 16; ++i) { int idx = rb_ + 32 * kb + (i & 3) + 8 * (i >> 2); idx = idx < 0 ? 0 : (idx > 256 ? 256 : idx); st[kb][i] += lut[idx]; }
;       }
.Ld0_far_a:
	s_or_b64 exec, exec, s[50:51]
	s_cmp_eq_u32 s67, 0
	s_cbranch_scc1 .Ld0_tree_a
	s_branch .Ld0_join_a
.Ld0_far_b:
	s_or_b64 exec, exec, s[40:41]
	s_branch .Ld0_join_b

; #define LAS __attribute__((address_space(3)))
; DI unsigned cvt_pk(float lo, float hi) { unsigned r; asm volatile("v_cvt_pk_bf16_f32 %0, %1, %2" : "=v"(r) : "v"(lo), "v"(hi)); return r; }
; DI float fexp2(float x) { return __builtin_amdgcn_exp2f(x); }
; template <int DK, int DV, int MODE> ...
;     ...
;     const float mabs = mx + mbase;
;     if (__any(mabs > mrun + ATT_THR)) {
;       const float mn = fmaxf(mrun, mabs), alpha = fexp2(mrun - mn); mrun = mn; lsum *= alpha;
; #pragma unroll
;       for (int db = 0; db < DV / 32; ++db)
; #pragma unroll
;         for (int i = 0; i < 16; ++i) O[db][i] *= alpha;
;     }
;     const float delta = mrun - mbase;
;     if (__any(delta != 0.f)) {
; #pragma unroll
;       for (int kb = 0; kb < 2; ++kb)
; #pragma unroll
;         for (int i = 0; i < 16; ++i) st[kb][i] -= delta;
;     }
;   };
;   auto part2 = [&](f32x16 (&st)[2], int t) __attribute__((always_inline)) {
;     float ps0 = 0.f, ps1 = 0.f, ps2 = 0.f, ps3 = 0.f;
; #pragma unroll
;     for (int kb = 0; kb < 2; ++kb)
; #pragma unroll
;       for (int i = 0; i < 16; i += 4) {
;         const float p0 = fexp2(st[kb][i]), p1 = fexp2(st[kb][i + 1]), p2 = fexp2(st[kb][i + 2]), p3 = fexp2(st[kb][i + 3]);
;         st[kb][i] = p0; st[kb][i + 1] = p1; st[kb][i + 2] = p2; st[kb][i + 3] = p3; ps0 += p0; ps1 += p1; ps2 += p2; ps3 += p3;
;       }
;     lsum += (ps0 + ps1) + (ps2 + ps3);
;     bf16x8 pf[2][2];
; #pragma unroll
;     for (int kb = 0; kb < 2; ++kb)
; #pragma unroll
;       for (int s = 0; s < 2; ++s) { u32x4 pp; pp.x = cvt_pk(st[kb][8 * s], st[kb][8 * s + 1]); pp.y = cvt_pk(st[kb][8 * s + 2], st[kb][8 * s + 3]); pp.z = cvt_pk(st[kb][8 * s + 4], st[kb][8 * s + 5]); pp.w = cvt_pk(st[kb][8 * s + 6], st[kb][8 * s + 7]); pf[kb][s] = __builtin_bit_cast(bf16x8, pp); }
; #pragma unroll
;     for (int db = 0; db < DV / 32; ++db)
; #pragma unroll
;       for (int kb = 0; kb < 2; ++kb)
; #pragma unroll
;         for (int s = 0; s < 2; ++s) {
;           if (MODE == 1 && ((kb == 1 && s == 1 && cwu == 0) || (kb == 0 && s == 0 && cwu != 0))) continue;
;           const bf16x8 vf = *(const LAS bf16x8*)(lds + ATT_VB + (t & 3) * VBUF + (32 * db + r) * VSTR + (2 * kb + s) * 32 + hh * 16);
;           O[db] = __builtin_amdgcn_mfma_f32_32x32x16_bf16(vf, pf[kb][s], O[db], 0, 0, 0);
;         }
;   };
.Ld1_join_a:
	v_pk_add_f32 v[2:3], v[190:191], v[174:175]
	s_nop 0
	v_cmp_gt_f32_e32 vcc, v2, v3
	s_cbranch_vccz .LBB0_179
	v_max_f32_e32 v0, v2, v2
	v_max_f32_e32 v2, v191, v191
	v_max_f32_e32 v2, v2, v0
	v_sub_f32_e32 v0, v191, v2
	v_exp_f32_e32 v0, v0
	v_mov_b32_e32 v191, v2
	v_mul_f32_e32 v239, v239, v0
	v_pk_mul_f32 v[78:79], v[78:79], v[0:1] op_sel_hi:[1,0]
	v_pk_mul_f32 v[76:77], v[76:77], v[0:1] op_sel_hi:[1,0]
	v_pk_mul_f32 v[74:75], v[74:75], v[0:1] op_sel_hi:[1,0]
	v_pk_mul_f32 v[72:73], v[72:73], v[0:1] op_sel_hi:[1,0]
	v_pk_mul_f32 v[70:71], v[70:71], v[0:1] op_sel_hi:[1,0]
	v_pk_mul_f32 v[68:69], v[68:69], v[0:1] op_sel_hi:[1,0]
	v_pk_mul_f32 v[66:67], v[66:67], v[0:1] op_sel_hi:[1,0]
	v_pk_mul_f32 v[64:65], v[64:65], v[0:1] op_sel_hi:[1,0]
	v_pk_mul_f32 v[62:63], v[62:63], v[0:1] op_sel_hi:[1,0]
	v_pk_mul_f32 v[60:61], v[60:61], v[0:1] op_sel_hi:[1,0]
	v_pk_mul_f32 v[58:59], v[58:59], v[0:1] op_sel_hi:[1,0]
	v_pk_mul_f32 v[56:57], v[56:57], v[0:1] op_sel_hi:[1,0]
	v_pk_mul_f32 v[54:55], v[54:55], v[0:1] op_sel_hi:[1,0]
	v_pk_mul_f32 v[52:53], v[52:53], v[0:1] op_sel_hi:[1,0]
	v_pk_mul_f32 v[50:51], v[50:51], v[0:1] op_sel_hi:[1,0]
	v_pk_mul_f32 v[48:49], v[48:49], v[0:1] op_sel_hi:[1,0]
	v_pk_mul_f32 v[46:47], v[46:47], v[0:1] op_sel_hi:[1,0]
	v_pk_mul_f32 v[44:45], v[44:45], v[0:1] op_sel_hi:[1,0]
	v_pk_mul_f32 v[42:43], v[42:43], v[0:1] op_sel_hi:[1,0]
	v_pk_mul_f32 v[40:41], v[40:41], v[0:1] op_sel_hi:[1,0]
	v_pk_mul_f32 v[38:39], v[38:39], v[0:1] op_sel_hi:[1,0]
	v_pk_mul_f32 v[36:37], v[36:37], v[0:1] op_sel_hi:[1,0]
	v_pk_mul_f32 v[34:35], v[34:35], v[0:1] op_sel_hi:[1,0]
	v_pk_mul_f32 v[32:33], v[32:33], v[0:1] op_sel_hi:[1,0]
	v_pk_mul_f32 v[30:31], v[30:31], v[0:1] op_sel_hi:[1,0]
	v_pk_mul_f32 v[28:29], v[28:29], v[0:1] op_sel_hi:[1,0]
	v_pk_mul_f32 v[26:27], v[26:27], v[0:1] op_sel_hi:[1,0]
	v_pk_mul_f32 v[24:25], v[24:25], v[0:1] op_sel_hi:[1,0]
	v_pk_mul_f32 v[22:23], v[22:23], v[0:1] op_sel_hi:[1,0]
	v_pk_mul_f32 v[20:21], v[20:21], v[0:1] op_sel_hi:[1,0]
	v_pk_mul_f32 v[18:19], v[18:19], v[0:1] op_sel_hi:[1,0]
	v_pk_mul_f32 v[16:17], v[16:17], v[0:1] op_sel_hi:[1,0]
.LBB0_179:
	v_sub_f32_e32 v0, v191, v190
	v_cmp_neq_f32_e32 vcc, 0, v0
	s_cbranch_vccz .LBB0_181
	v_pk_add_f32 v[96:97], v[96:97], v[0:1] op_sel_hi:[1,0] neg_lo:[0,1] neg_hi:[0,1]
	v_pk_add_f32 v[98:99], v[98:99], v[0:1] op_sel_hi:[1,0] neg_lo:[0,1] neg_hi:[0,1]
	v_pk_add_f32 v[100:101], v[100:101], v[0:1] op_sel_hi:[1,0] neg_lo:[0,1] neg_hi:[0,1]
	v_pk_add_f32 v[102:103], v[102:103], v[0:1] op_sel_hi:[1,0] neg_lo:[0,1] neg_hi:[0,1]
	v_pk_add_f32 v[104:105], v[104:105], v[0:1] op_sel_hi:[1,0] neg_lo:[0,1] neg_hi:[0,1]
	v_pk_add_f32 v[106:107], v[106:107], v[0:1] op_sel_hi:[1,0] neg_lo:[0,1] neg_hi:[0,1]
	v_pk_add_f32 v[108:109], v[108:109], v[0:1] op_sel_hi:[1,0] neg_lo:[0,1] neg_hi:[0,1]
	v_pk_add_f32 v[110:111], v[110:111], v[0:1] op_sel_hi:[1,0] neg_lo:[0,1] neg_hi:[0,1]
	v_pk_add_f32 v[80:81], v[80:81], v[0:1] op_sel_hi:[1,0] neg_lo:[0,1] neg_hi:[0,1]
	v_pk_add_f32 v[82:83], v[82:83], v[0:1] op_sel_hi:[1,0] neg_lo:[0,1] neg_hi:[0,1]
	v_pk_add_f32 v[84:85], v[84:85], v[0:1] op_sel_hi:[1,0] neg_lo:[0,1] neg_hi:[0,1]
	v_pk_add_f32 v[86:87], v[86:87], v[0:1] op_sel_hi:[1,0] neg_lo:[0,1] neg_hi:[0,1]
	v_pk_add_f32 v[88:89], v[88:89], v[0:1] op_sel_hi:[1,0] neg_lo:[0,1] neg_hi:[0,1]
	v_pk_add_f32 v[90:91], v[90:91], v[0:1] op_sel_hi:[1,0] neg_lo:[0,1] neg_hi:[0,1]
	v_pk_add_f32 v[92:93], v[92:93], v[0:1] op_sel_hi:[1,0] neg_lo:[0,1] neg_hi:[0,1]
	v_pk_add_f32 v[94:95], v[94:95], v[0:1] op_sel_hi:[1,0] neg_lo:[0,1] neg_hi:[0,1]
.LBB0_181:
	s_cmp_eq_u32 s32, 0
	s_cbranch_scc1 .Lstg_pre9
	s_waitcnt lgkmcnt(0)
	s_barrier
.Lstg_pre9:
	s_setprio 1
	s_add_i32 s28, s41, -4
	s_and_b32 s34, s28, 3
	s_mul_i32 s29, s34, 0x2400
	v_add_u32_e32 v3, s29, v233
	s_and_b32 s35, s50, 2
	s_mul_i32 s29, s35, 0x4800
	v_add_u32_e32 v224, s29, v235
	v_add_u32_e32 v224, 0xd000, v224
	ds_read_b128 v[4:7], v3
	ds_read_b128 v[8:11], v3 offset:32
	ds_read_b128 v[12:15], v3 offset:64
	ds_read_b128 v[196:199], v3 offset:96
	ds_read_b128 v[200:203], v3 offset:4608
	v_add_u32_e32 v0, 64, v240
	v_cmp_gt_i32_e64 s[46:47], s78, v0
	v_cmp_lt_i32_e32 vcc, s77, v0
	v_exp_f32_e32 v96, v96
	v_exp_f32_e32 v97, v97
	v_cndmask_b32_e64 v0, 0, v231, s[46:47]
	v_exp_f32_e32 v98, v98
	v_cndmask_b32_e32 v0, v0, v232, vcc
	v_cmp_neq_f32_e32 vcc, s53, v191
	v_exp_f32_e32 v99, v99
	v_exp_f32_e32 v100, v100
	v_exp_f32_e32 v101, v101
	v_cndmask_b32_e32 v2, 0, v191, vcc
	v_sub_f32_e32 v112, v0, v2
	v_mov_b32_e32 v113, v112
	v_mov_b32_e32 v114, v112
	v_mov_b32_e32 v115, v112
	v_mov_b32_e32 v116, v112
	v_mov_b32_e32 v117, v112
	v_mov_b32_e32 v118, v112
	v_mov_b32_e32 v119, v112
	v_mov_b32_e32 v120, v112
	v_mov_b32_e32 v121, v112
	v_mov_b32_e32 v122, v112
	v_mov_b32_e32 v123, v112
	v_mov_b32_e32 v124, v112
	v_mov_b32_e32 v125, v112
	v_mov_b32_e32 v126, v112
	v_mov_b32_e32 v127, v112
	v_exp_f32_e32 v102, v102
	v_exp_f32_e32 v103, v103
	s_waitcnt lgkmcnt(4)
	v_mfma_f32_32x32x16_bf16 v[128:143], v[4:7], v[144:147], v[112:127]
	ds_read_b128 v[4:7], v3 offset:4640
	v_add_f32_e32 v244, v96, v100
	v_add_f32_e32 v245, v97, v101
	v_add_f32_e32 v246, v98, v102
	v_add_f32_e32 v247, v99, v103
	v_cvt_pk_bf16_f32 v96, v96, v97
	v_cvt_pk_bf16_f32 v97, v98, v99
	v_cvt_pk_bf16_f32 v98, v100, v101
	s_waitcnt lgkmcnt(4)
	v_mfma_f32_32x32x16_bf16 v[128:143], v[8:11], v[148:151], v[128:143]
	ds_read_b128 v[8:11], v3 offset:4672
	v_cvt_pk_bf16_f32 v99, v102, v103
	v_exp_f32_e32 v104, v104
	v_exp_f32_e32 v105, v105
	v_exp_f32_e32 v106, v106
	s_waitcnt lgkmcnt(4)
; #define LAS __attribute__((address_space(3)))
; DI unsigned cvt_pk(float lo, float hi) { unsigned r; asm volatile("v_cvt_pk_bf16_f32 %0, %1, %2" : "=v"(r) : "v"(lo), "v"(hi)); return r; }
; DI float fexp2(float x) { return __builtin_amdgcn_exp2f(x); }
; template <int DK, int DV, int MODE> ...
;     ...
;     float mx = fmaxf(st[0][0], st[1][0]);
; #pragma unroll
;     for (int i = 1; i < 16; ++i) mx = fmaxf(fmaxf(mx, st[0][i]), st[1][i]);
;     mx = fmaxf(mx, __shfl_xor(mx, 32));
;     ...
;   auto part2 = [&](f32x16 (&st)[2], int t) __attribute__((always_inline)) {
;     float ps0 = 0.f, ps1 = 0.f, ps2 = 0.f, ps3 = 0.f;
; #pragma unroll
;     for (int kb = 0; kb < 2; ++kb)
; #pragma unroll
;       for (int i = 0; i < 16; i += 4) {
;         const float p0 = fexp2(st[kb][i]), p1 = fexp2(st[kb][i + 1]), p2 = fexp2(st[kb][i + 2]), p3 = fexp2(st[kb][i + 3]);
;         st[kb][i] = p0; st[kb][i + 1] = p1; st[kb][i + 2] = p2; st[kb][i + 3] = p3; ps0 += p0; ps1 += p1; ps2 += p2; ps3 += p3;
;       }
;     lsum += (ps0 + ps1) + (ps2 + ps3);
;     bf16x8 pf[2][2];
; #pragma unroll
;     for (int kb = 0; kb < 2; ++kb)
; #pragma unroll
;       for (int s = 0; s < 2; ++s) { u32x4 pp; pp.x = cvt_pk(st[kb][8 * s], st[kb][8 * s + 1]); pp.y = cvt_pk(st[kb][8 * s + 2], st[kb][8 * s + 3]); pp.z = cvt_pk(st[kb][8 * s + 4], st[kb][8 * s + 5]); pp.w = cvt_pk(st[kb][8 * s + 6], st[kb][8 * s + 7]); pf[kb][s] = __builtin_bit_cast(bf16x8, pp); }
; #pragma unroll
;     for (int db = 0; db < DV / 32; ++db)
; #pragma unroll
;       for (int kb = 0; kb < 2; ++kb)
; #pragma unroll
;         for (int s = 0; s < 2; ++s) {
;           if (MODE == 1 && ((kb == 1 && s == 1 && cwu == 0) || (kb == 0 && s == 0 && cwu != 0))) continue;
;           const bf16x8 vf = *(const LAS bf16x8*)(lds + ATT_VB + (t & 3) * VBUF + (32 * db + r) * VSTR + (2 * kb + s) * 32 + hh * 16);
;           O[db] = __builtin_amdgcn_mfma_f32_32x32x16_bf16(vf, pf[kb][s], O[db], 0, 0, 0);
;         }
;   };
	v_mfma_f32_32x32x16_bf16 v[128:143], v[12:15], v[152:155], v[128:143]
	ds_read_b128 v[12:15], v3 offset:4704
	v_exp_f32_e32 v107, v107
	v_exp_f32_e32 v108, v108
	v_exp_f32_e32 v109, v109
	v_exp_f32_e32 v110, v110
	s_waitcnt lgkmcnt(4)
	v_mfma_f32_32x32x16_bf16 v[128:143], v[196:199], v[156:159], v[128:143]
	ds_read_b128 v[196:199], v224
	v_exp_f32_e32 v111, v111
	v_add_f32_e32 v244, v104, v244
	v_add_f32_e32 v245, v105, v245
	v_add_f32_e32 v246, v106, v246
	v_add_f32_e32 v247, v107, v247
	v_add_f32_e32 v244, v108, v244
	s_waitcnt lgkmcnt(4)
	v_mfma_f32_32x32x16_bf16 v[112:127], v[200:203], v[144:147], v[112:127]
	ds_read_b128 v[200:203], v224 offset:4608
	v_add_f32_e32 v245, v109, v245
	v_add_f32_e32 v246, v110, v246
	v_add_f32_e32 v247, v111, v247
	v_cvt_pk_bf16_f32 v104, v104, v105
	v_cvt_pk_bf16_f32 v105, v106, v107
	v_cvt_pk_bf16_f32 v106, v108, v109
	v_cvt_pk_bf16_f32 v107, v110, v111
	s_waitcnt lgkmcnt(4)
	v_mfma_f32_32x32x16_bf16 v[112:127], v[4:7], v[148:151], v[112:127]
	ds_read_b128 v[4:7], v224 offset:9216
	v_exp_f32_e32 v80, v80
	v_exp_f32_e32 v81, v81
	v_exp_f32_e32 v82, v82
	v_exp_f32_e32 v83, v83
	s_waitcnt lgkmcnt(4)
	v_mfma_f32_32x32x16_bf16 v[112:127], v[8:11], v[152:155], v[112:127]
	ds_read_b128 v[8:11], v224 offset:13824
	v_exp_f32_e32 v84, v84
	v_exp_f32_e32 v85, v85
	v_exp_f32_e32 v86, v86
	v_exp_f32_e32 v87, v87
	s_waitcnt lgkmcnt(4)
	v_mfma_f32_32x32x16_bf16 v[112:127], v[12:15], v[156:159], v[112:127]
	ds_read_b128 v[12:15], v224 offset:32
	v_add_f32_e32 v244, v80, v244
	v_add_f32_e32 v245, v81, v245
	v_add_f32_e32 v246, v82, v246
	v_add_f32_e32 v247, v83, v247
	v_add_f32_e32 v244, v84, v244
	v_add_f32_e32 v245, v85, v245
	v_add_f32_e32 v246, v86, v246
	s_waitcnt lgkmcnt(4)
	v_mfma_f32_32x32x16_bf16 v[64:79], v[196:199], v[96:99], v[64:79]
	ds_read_b128 v[196:199], v224 offset:4640
	v_add_f32_e32 v247, v87, v247
	v_cvt_pk_bf16_f32 v80, v80, v81
	v_cvt_pk_bf16_f32 v81, v82, v83
	v_cvt_pk_bf16_f32 v82, v84, v85
	v_cvt_pk_bf16_f32 v83, v86, v87
	v_exp_f32_e32 v88, v88
	s_waitcnt lgkmcnt(4)
	v_mfma_f32_32x32x16_bf16 v[48:63], v[200:203], v[96:99], v[48:63]
	ds_read_b128 v[200:203], v224 offset:9248
	v_exp_f32_e32 v89, v89
	v_exp_f32_e32 v90, v90
	v_exp_f32_e32 v91, v91
	v_exp_f32_e32 v92, v92
	s_waitcnt lgkmcnt(4)
	v_mfma_f32_32x32x16_bf16 v[32:47], v[4:7], v[96:99], v[32:47]
	ds_read_b128 v[4:7], v224 offset:13856
	v_exp_f32_e32 v93, v93
	v_exp_f32_e32 v94, v94
	v_exp_f32_e32 v95, v95
	v_add_f32_e32 v244, v88, v244
	s_waitcnt lgkmcnt(4)
	v_mfma_f32_32x32x16_bf16 v[16:31], v[8:11], v[96:99], v[16:31]
	ds_read_b128 v[8:11], v224 offset:64
	v_add_f32_e32 v245, v89, v245
	v_add_f32_e32 v246, v90, v246
	v_add_f32_e32 v247, v91, v247
	v_add_f32_e32 v244, v92, v244
	v_add_f32_e32 v245, v93, v245
	v_add_f32_e32 v246, v94, v246
	v_add_f32_e32 v247, v95, v247
	s_waitcnt lgkmcnt(4)
	v_mfma_f32_32x32x16_bf16 v[64:79], v[12:15], v[104:107], v[64:79]
	ds_read_b128 v[12:15], v224 offset:4672
	v_cvt_pk_bf16_f32 v88, v88, v89
	v_cvt_pk_bf16_f32 v89, v90, v91
	v_cvt_pk_bf16_f32 v90, v92, v93
	v_cvt_pk_bf16_f32 v91, v94, v95
	v_add_f32_e32 v244, v244, v245
	v_add_f32_e32 v246, v246, v247
	v_max3_f32 v248, v128, v129, v130
	s_waitcnt lgkmcnt(4)
	v_mfma_f32_32x32x16_bf16 v[48:63], v[196:199], v[104:107], v[48:63]
	ds_read_b128 v[196:199], v224 offset:9280
	v_max3_f32 v249, v135, v136, v137
	v_max3_f32 v248, v248, v131, v132
	v_max3_f32 v249, v249, v138, v139
	v_max3_f32 v248, v248, v133, v134
	v_max3_f32 v249, v249, v140, v141
	v_max3_f32 v250, v112, v113, v114
	v_max3_f32 v251, v119, v120, v121
	s_waitcnt lgkmcnt(4)
	v_mfma_f32_32x32x16_bf16 v[32:47], v[200:203], v[104:107], v[32:47]
	ds_read_b128 v[200:203], v224 offset:13888
	v_max3_f32 v250, v250, v115, v116
	v_max3_f32 v251, v251, v122, v123
	v_max3_f32 v250, v250, v117, v118
	v_max3_f32 v251, v251, v124, v125
	v_max3_f32 v248, v248, v249, v142
	v_max3_f32 v250, v250, v251, v126
	v_max3_f32 v248, v248, v143, v127
	s_waitcnt lgkmcnt(4)
	v_mfma_f32_32x32x16_bf16 v[16:31], v[4:7], v[104:107], v[16:31]
	ds_read_b128 v[4:7], v224 offset:96
	v_max_f32_e32 v248, v248, v250
	v_mov_b32_e32 v249, v248
	s_waitcnt lgkmcnt(4)
	v_mfma_f32_32x32x16_bf16 v[64:79], v[8:11], v[80:83], v[64:79]
	ds_read_b128 v[8:11], v224 offset:4704
	s_waitcnt lgkmcnt(4)
	v_mfma_f32_32x32x16_bf16 v[48:63], v[12:15], v[80:83], v[48:63]
	ds_read_b128 v[12:15], v224 offset:9312
	s_waitcnt lgkmcnt(4)
	v_mfma_f32_32x32x16_bf16 v[32:47], v[196:199], v[80:83], v[32:47]
	ds_read_b128 v[196:199], v224 offset:13920
	s_waitcnt lgkmcnt(4)
	v_mfma_f32_32x32x16_bf16 v[16:31], v[200:203], v[80:83], v[16:31]
	s_waitcnt lgkmcnt(3)
	v_mfma_f32_32x32x16_bf16 v[64:79], v[4:7], v[88:91], v[64:79]
	s_waitcnt lgkmcnt(2)
	v_mfma_f32_32x32x16_bf16 v[48:63], v[8:11], v[88:91], v[48:63]
	s_waitcnt lgkmcnt(1)
	v_mfma_f32_32x32x16_bf16 v[32:47], v[12:15], v[88:91], v[32:47]
	s_waitcnt lgkmcnt(0)
	v_mfma_f32_32x32x16_bf16 v[16:31], v[196:199], v[88:91], v[16:31]
	v_add_f32_e32 v0, v244, v246
	v_add_f32_e32 v239, v239, v0
	v_permlane32_swap_b32 v248, v249
	v_max_f32_e32 v174, v248, v249
	s_setprio 0
	s_cmp_lg_u32 s32, 0
	s_cbranch_scc1 .Lstg_post10
	s_waitcnt lgkmcnt(0)
	s_barrier
.Lstg_post10:
	s_cmp_ge_u32 s28, s38
	s_cbranch_scc1 .LBB0_165
	s_and_saveexec_b64 s[28:29], s[26:27]
	s_cbranch_execz .LBB0_184
	s_mulk_i32 s35, 0x2400
	v_add_u32_e32 v0, s35, v183
	s_waitcnt vmcnt(0)
	ds_write_b128 v0, v[160:163]

; #define LAS __attribute__((address_space(3)))
; DI unsigned cvt_pk(float lo, float hi) { unsigned r; asm volatile("v_cvt_pk_bf16_f32 %0, %1, %2" : "=v"(r) : "v"(lo), "v"(hi)); return r; }
; DI float fexp2(float x) { return __builtin_amdgcn_exp2f(x); }
; template <int DK, int DV, int MODE> ...
;     ...
;     const float mabs = mx + mbase;
;     if (__any(mabs > mrun + ATT_THR)) {
;       const float mn = fmaxf(mrun, mabs), alpha = fexp2(mrun - mn); mrun = mn; lsum *= alpha;
; #pragma unroll
;       for (int db = 0; db < DV / 32; ++db)
; #pragma unroll
;         for (int i = 0; i < 16; ++i) O[db][i] *= alpha;
;     }
;     const float delta = mrun - mbase;
;     if (__any(delta != 0.f)) {
; #pragma unroll
;       for (int kb = 0; kb < 2; ++kb)
; #pragma unroll
;         for (int i = 0; i < 16; ++i) st[kb][i] -= delta;
;     }
;   };
;   auto part2 = [&](f32x16 (&st)[2], int t) __attribute__((always_inline)) {
;     float ps0 = 0.f, ps1 = 0.f, ps2 = 0.f, ps3 = 0.f;
; #pragma unroll
;     for (int kb = 0; kb < 2; ++kb)
; #pragma unroll
;       for (int i = 0; i < 16; i += 4) {
;         const float p0 = fexp2(st[kb][i]), p1 = fexp2(st[kb][i + 1]), p2 = fexp2(st[kb][i + 2]), p3 = fexp2(st[kb][i + 3]);
;         st[kb][i] = p0; st[kb][i + 1] = p1; st[kb][i + 2] = p2; st[kb][i + 3] = p3; ps0 += p0; ps1 += p1; ps2 += p2; ps3 += p3;
;       }
;     lsum += (ps0 + ps1) + (ps2 + ps3);
;     bf16x8 pf[2][2];
; #pragma unroll
;     for (int kb = 0; kb < 2; ++kb)
; #pragma unroll
;       for (int s = 0; s < 2; ++s) { u32x4 pp; pp.x = cvt_pk(st[kb][8 * s], st[kb][8 * s + 1]); pp.y = cvt_pk(st[kb][8 * s + 2], st[kb][8 * s + 3]); pp.z = cvt_pk(st[kb][8 * s + 4], st[kb][8 * s + 5]); pp.w = cvt_pk(st[kb][8 * s + 6], st[kb][8 * s + 7]); pf[kb][s] = __builtin_bit_cast(bf16x8, pp); }
; #pragma unroll
;     for (int db = 0; db < DV / 32; ++db)
; #pragma unroll
;       for (int kb = 0; kb < 2; ++kb)
; #pragma unroll
;         for (int s = 0; s < 2; ++s) {
;           if (MODE == 1 && ((kb == 1 && s == 1 && cwu == 0) || (kb == 0 && s == 0 && cwu != 0))) continue;
;           const bf16x8 vf = *(const LAS bf16x8*)(lds + ATT_VB + (t & 3) * VBUF + (32 * db + r) * VSTR + (2 * kb + s) * 32 + hh * 16);
;           O[db] = __builtin_amdgcn_mfma_f32_32x32x16_bf16(vf, pf[kb][s], O[db], 0, 0, 0);
;         }
;   };
.Ld1_join_b:
	v_mov_b32_e32 v3, v191
	v_pk_add_f32 v[4:5], v[2:3], v[174:175]
	s_nop 0
	v_cmp_gt_f32_e32 vcc, v4, v5
	s_cbranch_vccz .LBB0_192
	v_max_f32_e32 v0, v4, v4
	v_max_f32_e32 v3, v191, v191
	v_max_f32_e32 v3, v3, v0
	v_sub_f32_e32 v0, v191, v3
	v_exp_f32_e32 v0, v0
	v_mov_b32_e32 v191, v3
	v_mul_f32_e32 v239, v239, v0
	v_pk_mul_f32 v[78:79], v[78:79], v[0:1] op_sel_hi:[1,0]
	v_pk_mul_f32 v[76:77], v[76:77], v[0:1] op_sel_hi:[1,0]
	v_pk_mul_f32 v[74:75], v[74:75], v[0:1] op_sel_hi:[1,0]
	v_pk_mul_f32 v[72:73], v[72:73], v[0:1] op_sel_hi:[1,0]
	v_pk_mul_f32 v[70:71], v[70:71], v[0:1] op_sel_hi:[1,0]
	v_pk_mul_f32 v[68:69], v[68:69], v[0:1] op_sel_hi:[1,0]
	v_pk_mul_f32 v[66:67], v[66:67], v[0:1] op_sel_hi:[1,0]
	v_pk_mul_f32 v[64:65], v[64:65], v[0:1] op_sel_hi:[1,0]
	v_pk_mul_f32 v[62:63], v[62:63], v[0:1] op_sel_hi:[1,0]
	v_pk_mul_f32 v[60:61], v[60:61], v[0:1] op_sel_hi:[1,0]
	v_pk_mul_f32 v[58:59], v[58:59], v[0:1] op_sel_hi:[1,0]
	v_pk_mul_f32 v[56:57], v[56:57], v[0:1] op_sel_hi:[1,0]
	v_pk_mul_f32 v[54:55], v[54:55], v[0:1] op_sel_hi:[1,0]
	v_pk_mul_f32 v[52:53], v[52:53], v[0:1] op_sel_hi:[1,0]
	v_pk_mul_f32 v[50:51], v[50:51], v[0:1] op_sel_hi:[1,0]
	v_pk_mul_f32 v[48:49], v[48:49], v[0:1] op_sel_hi:[1,0]
	v_pk_mul_f32 v[46:47], v[46:47], v[0:1] op_sel_hi:[1,0]
	v_pk_mul_f32 v[44:45], v[44:45], v[0:1] op_sel_hi:[1,0]
	v_pk_mul_f32 v[42:43], v[42:43], v[0:1] op_sel_hi:[1,0]
	v_pk_mul_f32 v[40:41], v[40:41], v[0:1] op_sel_hi:[1,0]
	v_pk_mul_f32 v[38:39], v[38:39], v[0:1] op_sel_hi:[1,0]
	v_pk_mul_f32 v[36:37], v[36:37], v[0:1] op_sel_hi:[1,0]
	v_pk_mul_f32 v[34:35], v[34:35], v[0:1] op_sel_hi:[1,0]
	v_pk_mul_f32 v[32:33], v[32:33], v[0:1] op_sel_hi:[1,0]
	v_pk_mul_f32 v[30:31], v[30:31], v[0:1] op_sel_hi:[1,0]
	v_pk_mul_f32 v[28:29], v[28:29], v[0:1] op_sel_hi:[1,0]
	v_pk_mul_f32 v[26:27], v[26:27], v[0:1] op_sel_hi:[1,0]
	v_pk_mul_f32 v[24:25], v[24:25], v[0:1] op_sel_hi:[1,0]
	v_pk_mul_f32 v[22:23], v[22:23], v[0:1] op_sel_hi:[1,0]
	v_pk_mul_f32 v[20:21], v[20:21], v[0:1] op_sel_hi:[1,0]
	v_pk_mul_f32 v[18:19], v[18:19], v[0:1] op_sel_hi:[1,0]
	v_pk_mul_f32 v[16:17], v[16:17], v[0:1] op_sel_hi:[1,0]
.LBB0_192:
	v_sub_f32_e32 v0, v191, v2
	v_cmp_neq_f32_e32 vcc, 0, v0
	s_cbranch_vccz .LBB0_194
	v_pk_add_f32 v[128:129], v[128:129], v[0:1] op_sel_hi:[1,0] neg_lo:[0,1] neg_hi:[0,1]
	v_pk_add_f32 v[130:131], v[130:131], v[0:1] op_sel_hi:[1,0] neg_lo:[0,1] neg_hi:[0,1]
	v_pk_add_f32 v[132:133], v[132:133], v[0:1] op_sel_hi:[1,0] neg_lo:[0,1] neg_hi:[0,1]
	v_pk_add_f32 v[134:135], v[134:135], v[0:1] op_sel_hi:[1,0] neg_lo:[0,1] neg_hi:[0,1]
	v_pk_add_f32 v[136:137], v[136:137], v[0:1] op_sel_hi:[1,0] neg_lo:[0,1] neg_hi:[0,1]
	v_pk_add_f32 v[138:139], v[138:139], v[0:1] op_sel_hi:[1,0] neg_lo:[0,1] neg_hi:[0,1]
	v_pk_add_f32 v[140:141], v[140:141], v[0:1] op_sel_hi:[1,0] neg_lo:[0,1] neg_hi:[0,1]
	v_pk_add_f32 v[142:143], v[142:143], v[0:1] op_sel_hi:[1,0] neg_lo:[0,1] neg_hi:[0,1]
	v_pk_add_f32 v[112:113], v[112:113], v[0:1] op_sel_hi:[1,0] neg_lo:[0,1] neg_hi:[0,1]
	v_pk_add_f32 v[114:115], v[114:115], v[0:1] op_sel_hi:[1,0] neg_lo:[0,1] neg_hi:[0,1]
	v_pk_add_f32 v[116:117], v[116:117], v[0:1] op_sel_hi:[1,0] neg_lo:[0,1] neg_hi:[0,1]
	v_pk_add_f32 v[118:119], v[118:119], v[0:1] op_sel_hi:[1,0] neg_lo:[0,1] neg_hi:[0,1]
	v_pk_add_f32 v[120:121], v[120:121], v[0:1] op_sel_hi:[1,0] neg_lo:[0,1] neg_hi:[0,1]
	v_pk_add_f32 v[122:123], v[122:123], v[0:1] op_sel_hi:[1,0] neg_lo:[0,1] neg_hi:[0,1]
	v_pk_add_f32 v[124:125], v[124:125], v[0:1] op_sel_hi:[1,0] neg_lo:[0,1] neg_hi:[0,1]
	v_pk_add_f32 v[126:127], v[126:127], v[0:1] op_sel_hi:[1,0] neg_lo:[0,1] neg_hi:[0,1]
.LBB0_194:
	s_cmp_eq_u32 s32, 0
	s_cbranch_scc1 .Lstg_pre11
	s_waitcnt lgkmcnt(0)
	s_barrier
.Lstg_pre11:
	s_setprio 1
	s_and_b32 s20, s48, 2
	s_mulk_i32 s20, 0x2400
	s_mulk_i32 s34, 0x4800
	v_add_u32_e32 v3, s20, v233
	v_add_u32_e32 v224, s34, v235
	v_add_u32_e32 v224, 0xd000, v224
	ds_read_b128 v[4:7], v3
	ds_read_b128 v[8:11], v3 offset:32
	ds_read_b128 v[12:15], v3 offset:64
	ds_read_b128 v[196:199], v3 offset:96
	ds_read_b128 v[200:203], v3 offset:4608
	v_add_u32_e32 v0, 0x80, v240
	v_cmp_gt_i32_e32 vcc, s78, v0
	v_exp_f32_e32 v128, v128
	v_exp_f32_e32 v129, v129
	v_cndmask_b32_e32 v2, 0, v231, vcc
	v_cmp_lt_i32_e32 vcc, s77, v0
	v_exp_f32_e32 v130, v130
	v_exp_f32_e32 v131, v131
	v_cndmask_b32_e32 v0, v2, v232, vcc
	v_cmp_neq_f32_e32 vcc, s53, v191
	v_exp_f32_e32 v132, v132
	v_exp_f32_e32 v133, v133
	v_cndmask_b32_e32 v190, 0, v191, vcc
	v_sub_f32_e32 v80, v0, v190
	v_mov_b32_e32 v81, v80
	v_mov_b32_e32 v82, v80
	v_mov_b32_e32 v83, v80
	v_mov_b32_e32 v84, v80
	v_mov_b32_e32 v85, v80
	v_mov_b32_e32 v86, v80
	v_mov_b32_e32 v87, v80
	v_mov_b32_e32 v88, v80
	v_mov_b32_e32 v89, v80
	v_mov_b32_e32 v90, v80
	v_mov_b32_e32 v91, v80
	v_mov_b32_e32 v92, v80
	v_mov_b32_e32 v93, v80
	v_mov_b32_e32 v94, v80
	v_mov_b32_e32 v95, v80
	v_exp_f32_e32 v134, v134
	v_exp_f32_e32 v135, v135
	s_waitcnt lgkmcnt(4)
	v_mfma_f32_32x32x16_bf16 v[96:111], v[4:7], v[144:147], v[80:95]
	ds_read_b128 v[4:7], v3 offset:4640
	v_add_f32_e32 v244, v128, v132
	v_add_f32_e32 v245, v129, v133
	v_add_f32_e32 v246, v130, v134
	v_add_f32_e32 v247, v131, v135
	v_cvt_pk_bf16_f32 v128, v128, v129
	v_cvt_pk_bf16_f32 v129, v130, v131
	v_cvt_pk_bf16_f32 v130, v132, v133
	s_waitcnt lgkmcnt(4)
	v_mfma_f32_32x32x16_bf16 v[96:111], v[8:11], v[148:151], v[96:111]
	ds_read_b128 v[8:11], v3 offset:4672
	v_cvt_pk_bf16_f32 v131, v134, v135
	v_exp_f32_e32 v136, v136
	v_exp_f32_e32 v137, v137
	v_exp_f32_e32 v138, v138
	s_waitcnt lgkmcnt(4)
; #define LAS __attribute__((address_space(3)))
; DI unsigned cvt_pk(float lo, float hi) { unsigned r; asm volatile("v_cvt_pk_bf16_f32 %0, %1, %2" : "=v"(r) : "v"(lo), "v"(hi)); return r; }
; DI float fexp2(float x) { return __builtin_amdgcn_exp2f(x); }
; template <int DK, int DV, int MODE> ...
;     ...
;   auto part2 = [&](f32x16 (&st)[2], int t) __attribute__((always_inline)) {
;     float ps0 = 0.f, ps1 = 0.f, ps2 = 0.f, ps3 = 0.f;
; #pragma unroll
;     for (int kb = 0; kb < 2; ++kb)
; #pragma unroll
;       for (int i = 0; i < 16; i += 4) {
;         const float p0 = fexp2(st[kb][i]), p1 = fexp2(st[kb][i + 1]), p2 = fexp2(st[kb][i + 2]), p3 = fexp2(st[kb][i + 3]);
;         st[kb][i] = p0; st[kb][i + 1] = p1; st[kb][i + 2] = p2; st[kb][i + 3] = p3; ps0 += p0; ps1 += p1; ps2 += p2; ps3 += p3;
;       }
;     lsum += (ps0 + ps1) + (ps2 + ps3);
;     bf16x8 pf[2][2];
; #pragma unroll
;     for (int kb = 0; kb < 2; ++kb)
; #pragma unroll
;       for (int s = 0; s < 2; ++s) { u32x4 pp; pp.x = cvt_pk(st[kb][8 * s], st[kb][8 * s + 1]); pp.y = cvt_pk(st[kb][8 * s + 2], st[kb][8 * s + 3]); pp.z = cvt_pk(st[kb][8 * s + 4], st[kb][8 * s + 5]); pp.w = cvt_pk(st[kb][8 * s + 6], st[kb][8 * s + 7]); pf[kb][s] = __builtin_bit_cast(bf16x8, pp); }
; #pragma unroll
;     for (int db = 0; db < DV / 32; ++db)
; #pragma unroll
;       for (int kb = 0; kb < 2; ++kb)
; #pragma unroll
;         for (int s = 0; s < 2; ++s) {
;           if (MODE == 1 && ((kb == 1 && s == 1 && cwu == 0) || (kb == 0 && s == 0 && cwu != 0))) continue;
;           const bf16x8 vf = *(const LAS bf16x8*)(lds + ATT_VB + (t & 3) * VBUF + (32 * db + r) * VSTR + (2 * kb + s) * 32 + hh * 16);
;           O[db] = __builtin_amdgcn_mfma_f32_32x32x16_bf16(vf, pf[kb][s], O[db], 0, 0, 0);
;         }
;   };
	v_mfma_f32_32x32x16_bf16 v[96:111], v[12:15], v[152:155], v[96:111]
	ds_read_b128 v[12:15], v3 offset:4704
	v_exp_f32_e32 v139, v139
	v_exp_f32_e32 v140, v140
	v_exp_f32_e32 v141, v141
	v_exp_f32_e32 v142, v142
	s_waitcnt lgkmcnt(4)
	v_mfma_f32_32x32x16_bf16 v[96:111], v[196:199], v[156:159], v[96:111]
	ds_read_b128 v[196:199], v224
	v_exp_f32_e32 v143, v143
	v_add_f32_e32 v244, v136, v244
	v_add_f32_e32 v245, v137, v245
	v_add_f32_e32 v246, v138, v246
	v_add_f32_e32 v247, v139, v247
	v_add_f32_e32 v244, v140, v244
	s_waitcnt lgkmcnt(4)
	v_mfma_f32_32x32x16_bf16 v[80:95], v[200:203], v[144:147], v[80:95]
	ds_read_b128 v[200:203], v224 offset:4608
	v_add_f32_e32 v245, v141, v245
	v_add_f32_e32 v246, v142, v246
	v_add_f32_e32 v247, v143, v247
	v_cvt_pk_bf16_f32 v136, v136, v137
	v_cvt_pk_bf16_f32 v137, v138, v139
	v_cvt_pk_bf16_f32 v138, v140, v141
	v_cvt_pk_bf16_f32 v139, v142, v143
	s_waitcnt lgkmcnt(4)
	v_mfma_f32_32x32x16_bf16 v[80:95], v[4:7], v[148:151], v[80:95]
	ds_read_b128 v[4:7], v224 offset:9216
	v_exp_f32_e32 v112, v112
	v_exp_f32_e32 v113, v113
	v_exp_f32_e32 v114, v114
	v_exp_f32_e32 v115, v115
	s_waitcnt lgkmcnt(4)
	v_mfma_f32_32x32x16_bf16 v[80:95], v[8:11], v[152:155], v[80:95]
	ds_read_b128 v[8:11], v224 offset:13824
	v_exp_f32_e32 v116, v116
	v_exp_f32_e32 v117, v117
	v_exp_f32_e32 v118, v118
	v_exp_f32_e32 v119, v119
	s_waitcnt lgkmcnt(4)
	v_mfma_f32_32x32x16_bf16 v[80:95], v[12:15], v[156:159], v[80:95]
	ds_read_b128 v[12:15], v224 offset:32
	v_add_f32_e32 v244, v112, v244
	v_add_f32_e32 v245, v113, v245
	v_add_f32_e32 v246, v114, v246
	v_add_f32_e32 v247, v115, v247
	v_add_f32_e32 v244, v116, v244
	v_add_f32_e32 v245, v117, v245
	v_add_f32_e32 v246, v118, v246
	s_waitcnt lgkmcnt(4)
	v_mfma_f32_32x32x16_bf16 v[64:79], v[196:199], v[128:131], v[64:79]
	ds_read_b128 v[196:199], v224 offset:4640
	v_add_f32_e32 v247, v119, v247
	v_cvt_pk_bf16_f32 v112, v112, v113
	v_cvt_pk_bf16_f32 v113, v114, v115
	v_cvt_pk_bf16_f32 v114, v116, v117
	v_cvt_pk_bf16_f32 v115, v118, v119
	v_exp_f32_e32 v120, v120
	s_waitcnt lgkmcnt(4)
	v_mfma_f32_32x32x16_bf16 v[48:63], v[200:203], v[128:131], v[48:63]
	ds_read_b128 v[200:203], v224 offset:9248
	v_exp_f32_e32 v121, v121
	v_exp_f32_e32 v122, v122
	v_exp_f32_e32 v123, v123
	v_exp_f32_e32 v124, v124
	s_waitcnt lgkmcnt(4)
	v_mfma_f32_32x32x16_bf16 v[32:47], v[4:7], v[128:131], v[32:47]
	ds_read_b128 v[4:7], v224 offset:13856
	v_exp_f32_e32 v125, v125
	v_exp_f32_e32 v126, v126
	v_exp_f32_e32 v127, v127
	v_add_f32_e32 v244, v120, v244
	s_waitcnt lgkmcnt(4)
	v_mfma_f32_32x32x16_bf16 v[16:31], v[8:11], v[128:131], v[16:31]
	ds_read_b128 v[8:11], v224 offset:64
	v_add_f32_e32 v245, v121, v245
	v_add_f32_e32 v246, v122, v246
	v_add_f32_e32 v247, v123, v247
	v_add_f32_e32 v244, v124, v244
	v_add_f32_e32 v245, v125, v245
	v_add_f32_e32 v246, v126, v246
	v_add_f32_e32 v247, v127, v247
	s_waitcnt lgkmcnt(4)
	v_mfma_f32_32x32x16_bf16 v[64:79], v[12:15], v[136:139], v[64:79]
	ds_read_b128 v[12:15], v224 offset:4672
	v_cvt_pk_bf16_f32 v120, v120, v121
	v_cvt_pk_bf16_f32 v121, v122, v123
	v_cvt_pk_bf16_f32 v122, v124, v125
	v_cvt_pk_bf16_f32 v123, v126, v127
	v_add_f32_e32 v244, v244, v245
	v_add_f32_e32 v246, v246, v247
	v_max3_f32 v248, v96, v97, v98
	s_waitcnt lgkmcnt(4)
	v_mfma_f32_32x32x16_bf16 v[48:63], v[196:199], v[136:139], v[48:63]
	ds_read_b128 v[196:199], v224 offset:9280
	v_max3_f32 v249, v103, v104, v105
	v_max3_f32 v248, v248, v99, v100
	v_max3_f32 v249, v249, v106, v107
	v_max3_f32 v248, v248, v101, v102
	v_max3_f32 v249, v249, v108, v109
	v_max3_f32 v250, v80, v81, v82
	v_max3_f32 v251, v87, v88, v89
	s_waitcnt lgkmcnt(4)
	v_mfma_f32_32x32x16_bf16 v[32:47], v[200:203], v[136:139], v[32:47]
	ds_read_b128 v[200:203], v224 offset:13888
	v_max3_f32 v250, v250, v83, v84
	v_max3_f32 v251, v251, v90, v91
	v_max3_f32 v250, v250, v85, v86
	v_max3_f32 v251, v251, v92, v93
	v_max3_f32 v248, v248, v249, v110
	v_max3_f32 v250, v250, v251, v94
	v_max3_f32 v248, v248, v111, v95
	s_waitcnt lgkmcnt(4)
	v_mfma_f32_32x32x16_bf16 v[16:31], v[4:7], v[136:139], v[16:31]
	ds_read_b128 v[4:7], v224 offset:96
	v_max_f32_e32 v248, v248, v250
	v_mov_b32_e32 v249, v248
	s_waitcnt lgkmcnt(4)
	v_mfma_f32_32x32x16_bf16 v[64:79], v[8:11], v[112:115], v[64:79]
	ds_read_b128 v[8:11], v224 offset:4704
	s_waitcnt lgkmcnt(4)
	v_mfma_f32_32x32x16_bf16 v[48:63], v[12:15], v[112:115], v[48:63]
	ds_read_b128 v[12:15], v224 offset:9312
	s_waitcnt lgkmcnt(4)
	v_mfma_f32_32x32x16_bf16 v[32:47], v[196:199], v[112:115], v[32:47]
	ds_read_b128 v[196:199], v224 offset:13920
	s_waitcnt lgkmcnt(4)
	v_mfma_f32_32x32x16_bf16 v[16:31], v[200:203], v[112:115], v[16:31]
	s_waitcnt lgkmcnt(3)
	v_mfma_f32_32x32x16_bf16 v[64:79], v[4:7], v[120:123], v[64:79]
	s_waitcnt lgkmcnt(2)
	v_mfma_f32_32x32x16_bf16 v[48:63], v[8:11], v[120:123], v[48:63]
	s_waitcnt lgkmcnt(1)
	v_mfma_f32_32x32x16_bf16 v[32:47], v[12:15], v[120:123], v[32:47]
	s_waitcnt lgkmcnt(0)
	v_mfma_f32_32x32x16_bf16 v[16:31], v[196:199], v[120:123], v[16:31]
	v_add_f32_e32 v0, v244, v246
	v_add_f32_e32 v239, v239, v0
	v_permlane32_swap_b32 v248, v249
	v_max_f32_e32 v174, v248, v249
	s_setprio 0
	s_cmp_lg_u32 s32, 0
	s_cbranch_scc1 .Lstg_post12
	s_waitcnt lgkmcnt(0)
	s_barrier
.Lstg_post12:
	s_branch .LBB0_166
.LBB0_195:
	global_load_dwordx4 v[160:163], v[188:189], off
	s_or_b64 exec, exec, s[26:27]
	s_andn2_b64 vcc, exec, s[20:21]
	s_cbranch_vccnz .LBB0_188

; #define LAS __attribute__((address_space(3)))
; template <int DK, int DV, int MODE> ...
;     ...
;     if (MODE == 0) {
;       const int d0 = rel0 + 64 * t;
;       if (!(d0 - 31 >= 91) && !(d0 + 63 <= -91)) {
;         const int rb_ = d0 - r + 4 * hh + 128;
; #pragma unroll
;         for (int kb = 0; kb < 2; ++kb)
; #pragma unroll
;           for (int i = 0; i < 16; ++i) { int idx = rb_ + 32 * kb + (i & 3) + 8 * (i >> 2); idx = idx < 0 ? 0 : (idx > 256 ? 256 : idx); st[kb][i] += lut[idx]; }
;       }
;     } else {
;       const int ka = ka0 + t;
;       const LAS unsigned char* rp = (const LAS unsigned char*)lut + (ka - ri + 7) * 128;
; #pragma unroll
;       for (int q = 0; q < 8; ++q) { unsigned wv = nacolp[q]; asm volatile("" : "+v"(wv));
; #pragma unroll
;         for (int b4 = 0; b4 < 4; ++b4) { const int j = 4 * q + b4; st[j >> 4][j & 15] += *(const LAS float*)(rp + ((wv >> (8 * b4)) & 0xffu)); } }
;     }
;     float mx = fmaxf(st[0][0], st[1][0]);
; #pragma unroll
;     for (int i = 1; i < 16; ++i) mx = fmaxf(fmaxf(mx, st[0][i]), st[1][i]);
;     mx = fmaxf(mx, __shfl_xor(mx, 32));
.Ld1_far_a:
	s_or_b64 exec, exec, s[28:29]
	s_cmp_eq_u32 s40, 0
	s_cbranch_scc1 .Ld1_tree_a
	s_branch .Ld1_join_a
.Ld1_far_b:
	s_or_b64 exec, exec, s[20:21]
	s_branch .Ld1_join_b
